# v065 + GEMM K-loops issue 12 of 16 LDS-DMA pieces in saddr form (SGPR base + 32-bit VGPR offset), 8 per-iteration 64-bit VALU address adds removed per loop
# speedup vs baseline: 1.0096x; 1.0052x over previous
.LBB0_352:
	s_add_u32 s44, s42, 0xfff80080
	s_addc_u32 s45, s43, -1
	s_add_i32 s55, 0, 0x10000
	s_cmp_eq_u32 s54, 28
	s_cselect_b32 s53, s17, s45
	s_cselect_b32 s52, s18, s44
	v_add_u32_e32 v150, s55, v158
	s_cselect_b32 s45, s5, s33
	s_cselect_b32 s44, s20, s28
	s_add_i32 s61, 0, 0x14000
	ds_read_b128 v[130:133], v150
	ds_read_b128 v[160:163], v150 offset:1024
	ds_read_b128 v[164:167], v150 offset:2048
	ds_read_b128 v[168:171], v150 offset:3072
	v_add_u32_e32 v150, s61, v158
	ds_read_b128 v[172:175], v150
	ds_read_b128 v[176:179], v150 offset:1024
	ds_read_b128 v[180:183], v150 offset:2048
	ds_read_b128 v[184:187], v150 offset:3072
	s_add_i32 m0, s35, 0xc000
	ds_read_b128 v[188:191], v159
	ds_read_b128 v[192:195], v159 offset:1024
	ds_read_b128 v[196:199], v159 offset:2048
	ds_read_b128 v[210:213], v159 offset:3072
	ds_read_b128 v[214:217], v159 offset:4096
	ds_read_b128 v[218:221], v159 offset:5120
	ds_read_b128 v[222:225], v159 offset:6144
	ds_read_b128 v[226:229], v159 offset:7168
	global_load_lds_dwordx4 v146, s[42:43]
	s_add_i32 m0, s35, 0xe000
	s_nop 0
	global_load_lds_dwordx4 v148, s[42:43]
	v_cmp_ne_u32_e32 vcc, 0, v243
	s_cbranch_vccnz .Lrx_G_IN_0
	s_waitcnt vmcnt(8)
.Lrx_G_IN_0:
	s_waitcnt vmcnt(16)
	s_waitcnt lgkmcnt(0)
	s_setprio 1
	s_barrier
	v_mfma_f32_16x16x32_bf16 v[126:129], v[130:133], v[188:191], v[126:129]
	v_mfma_f32_16x16x32_bf16 v[122:125], v[164:167], v[188:191], v[122:125]
	v_mfma_f32_16x16x32_bf16 v[110:113], v[130:133], v[196:199], v[110:113]
	v_mfma_f32_16x16x32_bf16 v[106:109], v[164:167], v[196:199], v[106:109]
	v_mfma_f32_16x16x32_bf16 v[92:95], v[130:133], v[214:217], v[92:95]
	v_mfma_f32_16x16x32_bf16 v[88:91], v[164:167], v[214:217], v[88:91]
	v_mfma_f32_16x16x32_bf16 v[76:79], v[130:133], v[222:225], v[76:79]
	v_mfma_f32_16x16x32_bf16 v[72:75], v[164:167], v[222:225], v[72:75]
	v_mfma_f32_16x16x32_bf16 v[126:129], v[160:163], v[192:195], v[126:129]
	v_mfma_f32_16x16x32_bf16 v[122:125], v[168:171], v[192:195], v[122:125]
	v_mfma_f32_16x16x32_bf16 v[110:113], v[160:163], v[210:213], v[110:113]
	v_mfma_f32_16x16x32_bf16 v[106:109], v[168:171], v[210:213], v[106:109]
	v_mfma_f32_16x16x32_bf16 v[92:95], v[160:163], v[218:221], v[92:95]
	v_mfma_f32_16x16x32_bf16 v[88:91], v[168:171], v[218:221], v[88:91]
	v_mfma_f32_16x16x32_bf16 v[76:79], v[160:163], v[226:229], v[76:79]
	v_mfma_f32_16x16x32_bf16 v[72:75], v[168:171], v[226:229], v[72:75]
	v_mfma_f32_16x16x32_bf16 v[118:121], v[172:175], v[188:191], v[118:121]
	v_mfma_f32_16x16x32_bf16 v[114:117], v[180:183], v[188:191], v[114:117]
	v_mfma_f32_16x16x32_bf16 v[102:105], v[172:175], v[196:199], v[102:105]
	v_mfma_f32_16x16x32_bf16 v[98:101], v[180:183], v[196:199], v[98:101]
	v_mfma_f32_16x16x32_bf16 v[84:87], v[172:175], v[214:217], v[84:87]
	v_mfma_f32_16x16x32_bf16 v[80:83], v[180:183], v[214:217], v[80:83]
	v_mfma_f32_16x16x32_bf16 v[68:71], v[172:175], v[222:225], v[68:71]
	v_mfma_f32_16x16x32_bf16 v[64:67], v[180:183], v[222:225], v[64:67]
	v_mfma_f32_16x16x32_bf16 v[118:121], v[176:179], v[192:195], v[118:121]
	v_mfma_f32_16x16x32_bf16 v[114:117], v[184:187], v[192:195], v[114:117]
	v_mfma_f32_16x16x32_bf16 v[102:105], v[176:179], v[210:213], v[102:105]
	v_mfma_f32_16x16x32_bf16 v[98:101], v[184:187], v[210:213], v[98:101]
	v_mfma_f32_16x16x32_bf16 v[84:87], v[176:179], v[218:221], v[84:87]
	v_mfma_f32_16x16x32_bf16 v[80:83], v[184:187], v[218:221], v[80:83]
	v_mfma_f32_16x16x32_bf16 v[68:71], v[176:179], v[226:229], v[68:71]
	v_mfma_f32_16x16x32_bf16 v[64:67], v[184:187], v[226:229], v[64:67]
	s_barrier
	s_setprio 0
	s_add_i32 s55, s55, s75
	v_lshl_add_u64 v[150:151], s[44:45], 0, v[142:143]
	s_mov_b32 m0, s55
	ds_read_b128 v[188:191], v159 offset:16384
	ds_read_b128 v[192:195], v159 offset:17408
	ds_read_b128 v[196:199], v159 offset:18432
	ds_read_b128 v[210:213], v159 offset:19456
	ds_read_b128 v[214:217], v159 offset:20480
	ds_read_b128 v[218:221], v159 offset:21504
	ds_read_b128 v[222:225], v159 offset:22528
	ds_read_b128 v[226:229], v159 offset:23552
	global_load_lds_dwordx4 v142, s[44:45]
	s_add_i32 m0, s55, 0x2000
	s_add_u32 s56, s44, 0x80000
	v_lshl_add_u64 v[154:155], s[44:45], 0, v[138:139]
	s_addc_u32 s57, s45, 0
	s_add_i32 s55, s61, s75
	global_load_lds_dwordx4 v138, s[44:45]
	s_mov_b32 m0, s55
	v_lshl_add_u64 v[202:203], s[52:53], 0, v[140:141]
	global_load_lds_dwordx4 v142, s[56:57]
	s_add_i32 m0, s55, 0x2000
	s_nop 0
	global_load_lds_dwordx4 v138, s[56:57]
	v_lshl_add_u64 v[156:157], s[52:53], 0, v[144:145]
	s_mov_b32 m0, s35
	s_nop 0
	global_load_lds_dwordx4 v144, s[52:53]
	s_mov_b32 m0, s68
	s_nop 0
	global_load_lds_dwordx4 v140, s[52:53]
	v_cmp_ne_u32_e32 vcc, 0, v243
	s_cbranch_vccnz .Lrx_G_IN_1
	s_waitcnt vmcnt(8)
.Lrx_G_IN_1:
	s_waitcnt vmcnt(16)
	v_mov_b32_e32 v243, 0
	s_waitcnt lgkmcnt(0)
	s_setprio 1
	s_barrier
	v_mfma_f32_16x16x32_bf16 v[60:63], v[130:133], v[188:191], v[60:63]
	v_mfma_f32_16x16x32_bf16 v[56:59], v[164:167], v[188:191], v[56:59]
	v_mfma_f32_16x16x32_bf16 v[44:47], v[130:133], v[196:199], v[44:47]
	v_mfma_f32_16x16x32_bf16 v[40:43], v[164:167], v[196:199], v[40:43]
	v_mfma_f32_16x16x32_bf16 v[28:31], v[130:133], v[214:217], v[28:31]
	v_mfma_f32_16x16x32_bf16 v[24:27], v[164:167], v[214:217], v[24:27]
	v_mfma_f32_16x16x32_bf16 v[12:15], v[130:133], v[222:225], v[12:15]
	v_mfma_f32_16x16x32_bf16 v[8:11], v[164:167], v[222:225], v[8:11]
	v_mfma_f32_16x16x32_bf16 v[60:63], v[160:163], v[192:195], v[60:63]
	v_mfma_f32_16x16x32_bf16 v[56:59], v[168:171], v[192:195], v[56:59]
	v_mfma_f32_16x16x32_bf16 v[44:47], v[160:163], v[210:213], v[44:47]
	v_mfma_f32_16x16x32_bf16 v[40:43], v[168:171], v[210:213], v[40:43]
	v_mfma_f32_16x16x32_bf16 v[28:31], v[160:163], v[218:221], v[28:31]
	v_mfma_f32_16x16x32_bf16 v[24:27], v[168:171], v[218:221], v[24:27]
	v_mfma_f32_16x16x32_bf16 v[12:15], v[160:163], v[226:229], v[12:15]
	v_mfma_f32_16x16x32_bf16 v[8:11], v[168:171], v[226:229], v[8:11]
	v_mfma_f32_16x16x32_bf16 v[52:55], v[172:175], v[188:191], v[52:55]
	v_mfma_f32_16x16x32_bf16 v[48:51], v[180:183], v[188:191], v[48:51]
	v_mfma_f32_16x16x32_bf16 v[36:39], v[172:175], v[196:199], v[36:39]
	v_mfma_f32_16x16x32_bf16 v[32:35], v[180:183], v[196:199], v[32:35]
	v_mfma_f32_16x16x32_bf16 v[20:23], v[172:175], v[214:217], v[20:23]
	v_mfma_f32_16x16x32_bf16 v[16:19], v[180:183], v[214:217], v[16:19]
	v_mfma_f32_16x16x32_bf16 v[4:7], v[172:175], v[222:225], v[4:7]
	v_mfma_f32_16x16x32_bf16 v[0:3], v[180:183], v[222:225], v[0:3]
	v_mfma_f32_16x16x32_bf16 v[52:55], v[176:179], v[192:195], v[52:55]
	v_mfma_f32_16x16x32_bf16 v[48:51], v[184:187], v[192:195], v[48:51]
	v_mfma_f32_16x16x32_bf16 v[36:39], v[176:179], v[210:213], v[36:39]
	v_mfma_f32_16x16x32_bf16 v[32:35], v[184:187], v[210:213], v[32:35]
	v_mfma_f32_16x16x32_bf16 v[20:23], v[176:179], v[218:221], v[20:23]
	v_mfma_f32_16x16x32_bf16 v[16:19], v[184:187], v[218:221], v[16:19]
	v_mfma_f32_16x16x32_bf16 v[4:7], v[176:179], v[226:229], v[4:7]
	v_mfma_f32_16x16x32_bf16 v[0:3], v[184:187], v[226:229], v[0:3]
	s_barrier
	s_setprio 0
	s_add_i32 s55, 0, 0x18000
	s_add_i32 s56, 0, 0x1c000
	v_add_u32_e32 v168, s55, v158
	v_add_u32_e32 v184, s56, v158
	ds_read_b128 v[130:133], v168
	ds_read_b128 v[160:163], v168 offset:1024
	ds_read_b128 v[164:167], v168 offset:2048
	ds_read_b128 v[168:171], v168 offset:3072
	ds_read_b128 v[172:175], v184
	ds_read_b128 v[176:179], v184 offset:1024
	ds_read_b128 v[180:183], v184 offset:2048
	ds_read_b128 v[184:187], v184 offset:3072
	s_add_u32 s52, s52, 0x80000
	s_addc_u32 s53, s53, 0
	s_mov_b32 m0, s69
	ds_read_b128 v[188:191], v159 offset:32768
	ds_read_b128 v[192:195], v159 offset:33792
	ds_read_b128 v[196:199], v159 offset:34816
	ds_read_b128 v[210:213], v159 offset:35840
	ds_read_b128 v[214:217], v159 offset:36864
	ds_read_b128 v[218:221], v159 offset:37888
	ds_read_b128 v[222:225], v159 offset:38912
	ds_read_b128 v[226:229], v159 offset:39936
	global_load_lds_dwordx4 v144, s[52:53]
	s_mov_b32 m0, s77
	s_nop 0
	global_load_lds_dwordx4 v140, s[52:53]
	s_waitcnt vmcnt(8)
	s_waitcnt lgkmcnt(0)
	s_setprio 1
	s_barrier
	v_mfma_f32_16x16x32_bf16 v[126:129], v[130:133], v[188:191], v[126:129]
	v_mfma_f32_16x16x32_bf16 v[122:125], v[164:167], v[188:191], v[122:125]
	v_mfma_f32_16x16x32_bf16 v[110:113], v[130:133], v[196:199], v[110:113]
	v_mfma_f32_16x16x32_bf16 v[106:109], v[164:167], v[196:199], v[106:109]
	v_mfma_f32_16x16x32_bf16 v[92:95], v[130:133], v[214:217], v[92:95]
	v_mfma_f32_16x16x32_bf16 v[88:91], v[164:167], v[214:217], v[88:91]
	v_mfma_f32_16x16x32_bf16 v[76:79], v[130:133], v[222:225], v[76:79]
	v_mfma_f32_16x16x32_bf16 v[72:75], v[164:167], v[222:225], v[72:75]
	v_mfma_f32_16x16x32_bf16 v[126:129], v[160:163], v[192:195], v[126:129]
	v_mfma_f32_16x16x32_bf16 v[122:125], v[168:171], v[192:195], v[122:125]
	v_mfma_f32_16x16x32_bf16 v[110:113], v[160:163], v[210:213], v[110:113]
	v_mfma_f32_16x16x32_bf16 v[106:109], v[168:171], v[210:213], v[106:109]
	v_mfma_f32_16x16x32_bf16 v[92:95], v[160:163], v[218:221], v[92:95]
	v_mfma_f32_16x16x32_bf16 v[88:91], v[168:171], v[218:221], v[88:91]
	v_mfma_f32_16x16x32_bf16 v[76:79], v[160:163], v[226:229], v[76:79]
	v_mfma_f32_16x16x32_bf16 v[72:75], v[168:171], v[226:229], v[72:75]
	v_mfma_f32_16x16x32_bf16 v[118:121], v[172:175], v[188:191], v[118:121]
	v_mfma_f32_16x16x32_bf16 v[114:117], v[180:183], v[188:191], v[114:117]
	v_mfma_f32_16x16x32_bf16 v[102:105], v[172:175], v[196:199], v[102:105]
	v_mfma_f32_16x16x32_bf16 v[98:101], v[180:183], v[196:199], v[98:101]
	v_mfma_f32_16x16x32_bf16 v[84:87], v[172:175], v[214:217], v[84:87]
	v_mfma_f32_16x16x32_bf16 v[80:83], v[180:183], v[214:217], v[80:83]
	v_mfma_f32_16x16x32_bf16 v[68:71], v[172:175], v[222:225], v[68:71]
	v_mfma_f32_16x16x32_bf16 v[64:67], v[180:183], v[222:225], v[64:67]
	v_mfma_f32_16x16x32_bf16 v[118:121], v[176:179], v[192:195], v[118:121]
	v_mfma_f32_16x16x32_bf16 v[114:117], v[184:187], v[192:195], v[114:117]
	v_mfma_f32_16x16x32_bf16 v[102:105], v[176:179], v[210:213], v[102:105]
	v_mfma_f32_16x16x32_bf16 v[98:101], v[184:187], v[210:213], v[98:101]
	v_mfma_f32_16x16x32_bf16 v[84:87], v[176:179], v[218:221], v[84:87]
	v_mfma_f32_16x16x32_bf16 v[80:83], v[184:187], v[218:221], v[80:83]
	v_mfma_f32_16x16x32_bf16 v[68:71], v[176:179], v[226:229], v[68:71]
	v_mfma_f32_16x16x32_bf16 v[64:67], v[184:187], v[226:229], v[64:67]
	s_barrier
	s_setprio 0
	s_add_i32 s52, s55, s75
	v_lshl_add_u64 v[150:151], v[150:151], 0, s[64:65]
	s_mov_b32 m0, s52
	ds_read_b128 v[188:191], v159 offset:49152
	ds_read_b128 v[192:195], v159 offset:50176
	ds_read_b128 v[196:199], v159 offset:51200
	ds_read_b128 v[210:213], v159 offset:52224
	ds_read_b128 v[214:217], v159 offset:53248
	ds_read_b128 v[218:221], v159 offset:54272
	ds_read_b128 v[222:225], v159 offset:55296
	ds_read_b128 v[226:229], v159 offset:56320
	global_load_lds_dwordx4 v[150:151], off
	s_add_i32 m0, s52, 0x2000
	s_add_u32 s44, s44, 0x80080
	v_lshl_add_u64 v[150:151], v[154:155], 0, s[64:65]
	s_addc_u32 s45, s45, 0
	s_add_i32 s52, s56, s75
	global_load_lds_dwordx4 v[150:151], off
	s_mov_b32 m0, s52
	s_nop 0
	global_load_lds_dwordx4 v142, s[44:45]
	s_add_i32 m0, s52, 0x2000
	s_nop 0
	global_load_lds_dwordx4 v138, s[44:45]
	v_lshl_add_u64 v[150:151], v[156:157], 0, s[64:65]
	s_mov_b32 m0, s79
	s_nop 0
	global_load_lds_dwordx4 v[150:151], off
	v_lshl_add_u64 v[150:151], v[202:203], 0, s[64:65]
	s_mov_b32 m0, s81
	s_nop 0
	global_load_lds_dwordx4 v[150:151], off
	s_waitcnt vmcnt(8)
	s_waitcnt lgkmcnt(0)
	s_setprio 1
	s_barrier
	v_mfma_f32_16x16x32_bf16 v[60:63], v[130:133], v[188:191], v[60:63]
	v_mfma_f32_16x16x32_bf16 v[56:59], v[164:167], v[188:191], v[56:59]
	v_mfma_f32_16x16x32_bf16 v[44:47], v[130:133], v[196:199], v[44:47]
	v_mfma_f32_16x16x32_bf16 v[40:43], v[164:167], v[196:199], v[40:43]
	v_mfma_f32_16x16x32_bf16 v[28:31], v[130:133], v[214:217], v[28:31]
	v_mfma_f32_16x16x32_bf16 v[24:27], v[164:167], v[214:217], v[24:27]
	v_mfma_f32_16x16x32_bf16 v[12:15], v[130:133], v[222:225], v[12:15]
	v_mfma_f32_16x16x32_bf16 v[8:11], v[164:167], v[222:225], v[8:11]
	v_mfma_f32_16x16x32_bf16 v[60:63], v[160:163], v[192:195], v[60:63]
	v_mfma_f32_16x16x32_bf16 v[56:59], v[168:171], v[192:195], v[56:59]
	v_mfma_f32_16x16x32_bf16 v[44:47], v[160:163], v[210:213], v[44:47]
	v_mfma_f32_16x16x32_bf16 v[40:43], v[168:171], v[210:213], v[40:43]
	v_mfma_f32_16x16x32_bf16 v[28:31], v[160:163], v[218:221], v[28:31]
	v_mfma_f32_16x16x32_bf16 v[24:27], v[168:171], v[218:221], v[24:27]
	v_mfma_f32_16x16x32_bf16 v[12:15], v[160:163], v[226:229], v[12:15]
	v_mfma_f32_16x16x32_bf16 v[8:11], v[168:171], v[226:229], v[8:11]
	v_mfma_f32_16x16x32_bf16 v[52:55], v[172:175], v[188:191], v[52:55]
	v_mfma_f32_16x16x32_bf16 v[48:51], v[180:183], v[188:191], v[48:51]
	v_mfma_f32_16x16x32_bf16 v[36:39], v[172:175], v[196:199], v[36:39]
	v_mfma_f32_16x16x32_bf16 v[32:35], v[180:183], v[196:199], v[32:35]
	v_mfma_f32_16x16x32_bf16 v[20:23], v[172:175], v[214:217], v[20:23]
	v_mfma_f32_16x16x32_bf16 v[16:19], v[180:183], v[214:217], v[16:19]
	v_mfma_f32_16x16x32_bf16 v[4:7], v[172:175], v[222:225], v[4:7]
	v_mfma_f32_16x16x32_bf16 v[0:3], v[180:183], v[222:225], v[0:3]
	v_mfma_f32_16x16x32_bf16 v[52:55], v[176:179], v[192:195], v[52:55]
	v_mfma_f32_16x16x32_bf16 v[48:51], v[184:187], v[192:195], v[48:51]
	v_mfma_f32_16x16x32_bf16 v[36:39], v[176:179], v[210:213], v[36:39]
	v_mfma_f32_16x16x32_bf16 v[32:35], v[184:187], v[210:213], v[32:35]
	v_mfma_f32_16x16x32_bf16 v[20:23], v[176:179], v[218:221], v[20:23]
	v_mfma_f32_16x16x32_bf16 v[16:19], v[184:187], v[218:221], v[16:19]
	v_mfma_f32_16x16x32_bf16 v[4:7], v[176:179], v[226:229], v[4:7]
	v_mfma_f32_16x16x32_bf16 v[0:3], v[184:187], v[226:229], v[0:3]
	s_barrier
	s_setprio 0
	s_add_i32 s54, s54, 2
	s_add_u32 s42, s42, 0x100
	s_addc_u32 s43, s43, 0
	s_add_u32 s28, s28, 0x100
	s_addc_u32 s33, s33, 0
	s_cmp_gt_u32 s54, 29
	s_cbranch_scc0 .LBB0_352
	v_mov_b32_e32 v243, 1
	v_readlane_b32 s6, v251, 54
	v_readlane_b32 s7, v251, 55
	s_and_b64 vcc, exec, s[6:7]
	s_cbranch_vccz .LBB0_355
	s_barrier

.LBB0_636:
	s_add_u32 s56, s68, 0xfffe0080
	s_addc_u32 s57, s69, -1
	s_add_i32 s58, 0, 0x10000
	s_cmp_eq_u32 s55, 4
	s_cselect_b32 s85, s35, s57
	s_cselect_b32 s84, s43, s56
	v_add_u32_e32 v145, s58, v142
	s_cselect_b32 s83, s31, s54
	s_cselect_b32 s82, s50, s51
	s_add_i32 s59, 0, 0x14000
	ds_read_b128 v[146:149], v145
	ds_read_b128 v[150:153], v145 offset:1024
	ds_read_b128 v[158:161], v145 offset:2048
	ds_read_b128 v[162:165], v145 offset:3072
	v_add_u32_e32 v145, s59, v142
	ds_read_b128 v[166:169], v145
	ds_read_b128 v[170:173], v145 offset:1024
	ds_read_b128 v[174:177], v145 offset:2048
	ds_read_b128 v[178:181], v145 offset:3072
	s_add_i32 m0, s10, 0xc000
	ds_read_b128 v[182:185], v144
	ds_read_b128 v[186:189], v144 offset:1024
	ds_read_b128 v[190:193], v144 offset:2048
	ds_read_b128 v[194:197], v144 offset:3072
	ds_read_b128 v[210:213], v144 offset:4096
	ds_read_b128 v[214:217], v144 offset:5120
	ds_read_b128 v[218:221], v144 offset:6144
	ds_read_b128 v[222:225], v144 offset:7168
	global_load_lds_dwordx4 v136, s[68:69]
	s_add_i32 m0, s10, 0xe000
	s_nop 0
	global_load_lds_dwordx4 v138, s[68:69]
	v_cmp_ne_u32_e32 vcc, 0, v243
	s_cbranch_vccnz .Lrx_uq_0
	s_waitcnt vmcnt(8)
.Lrx_uq_0:
	s_waitcnt vmcnt(24)
	s_waitcnt lgkmcnt(0)
	s_setprio 1
	s_barrier
	v_mfma_f32_16x16x32_bf16 v[126:129], v[146:149], v[182:185], v[126:129]
	v_mfma_f32_16x16x32_bf16 v[122:125], v[158:161], v[182:185], v[122:125]
	v_mfma_f32_16x16x32_bf16 v[118:121], v[146:149], v[190:193], v[118:121]
	v_mfma_f32_16x16x32_bf16 v[114:117], v[158:161], v[190:193], v[114:117]
	v_mfma_f32_16x16x32_bf16 v[102:105], v[146:149], v[210:213], v[102:105]
	v_mfma_f32_16x16x32_bf16 v[98:101], v[158:161], v[210:213], v[98:101]
	v_mfma_f32_16x16x32_bf16 v[84:87], v[146:149], v[218:221], v[84:87]
	v_mfma_f32_16x16x32_bf16 v[80:83], v[158:161], v[218:221], v[80:83]
	v_mfma_f32_16x16x32_bf16 v[126:129], v[150:153], v[186:189], v[126:129]
	v_mfma_f32_16x16x32_bf16 v[122:125], v[162:165], v[186:189], v[122:125]
	v_mfma_f32_16x16x32_bf16 v[118:121], v[150:153], v[194:197], v[118:121]
	v_mfma_f32_16x16x32_bf16 v[114:117], v[162:165], v[194:197], v[114:117]
	v_mfma_f32_16x16x32_bf16 v[102:105], v[150:153], v[214:217], v[102:105]
	v_mfma_f32_16x16x32_bf16 v[98:101], v[162:165], v[214:217], v[98:101]
	v_mfma_f32_16x16x32_bf16 v[84:87], v[150:153], v[222:225], v[84:87]
	v_mfma_f32_16x16x32_bf16 v[80:83], v[162:165], v[222:225], v[80:83]
	v_mfma_f32_16x16x32_bf16 v[110:113], v[166:169], v[182:185], v[110:113]
	v_mfma_f32_16x16x32_bf16 v[106:109], v[174:177], v[182:185], v[106:109]
	v_mfma_f32_16x16x32_bf16 v[92:95], v[166:169], v[190:193], v[92:95]
	v_mfma_f32_16x16x32_bf16 v[88:91], v[174:177], v[190:193], v[88:91]
	v_mfma_f32_16x16x32_bf16 v[76:79], v[166:169], v[210:213], v[76:79]
	v_mfma_f32_16x16x32_bf16 v[72:75], v[174:177], v[210:213], v[72:75]
	v_mfma_f32_16x16x32_bf16 v[68:71], v[166:169], v[218:221], v[68:71]
	v_mfma_f32_16x16x32_bf16 v[64:67], v[174:177], v[218:221], v[64:67]
	v_mfma_f32_16x16x32_bf16 v[110:113], v[170:173], v[186:189], v[110:113]
	v_mfma_f32_16x16x32_bf16 v[106:109], v[178:181], v[186:189], v[106:109]
	v_mfma_f32_16x16x32_bf16 v[92:95], v[170:173], v[194:197], v[92:95]
	v_mfma_f32_16x16x32_bf16 v[88:91], v[178:181], v[194:197], v[88:91]
	v_mfma_f32_16x16x32_bf16 v[76:79], v[170:173], v[214:217], v[76:79]
	v_mfma_f32_16x16x32_bf16 v[72:75], v[178:181], v[214:217], v[72:75]
	v_mfma_f32_16x16x32_bf16 v[68:71], v[170:173], v[222:225], v[68:71]
	v_mfma_f32_16x16x32_bf16 v[64:67], v[178:181], v[222:225], v[64:67]
	s_barrier
	s_setprio 0
	s_add_i32 s56, s58, s75
	v_lshl_add_u64 v[154:155], s[82:83], 0, v[96:97]
	s_mov_b32 m0, s56
	ds_read_b128 v[182:185], v144 offset:16384
	ds_read_b128 v[186:189], v144 offset:17408
	ds_read_b128 v[190:193], v144 offset:18432
	ds_read_b128 v[194:197], v144 offset:19456
	ds_read_b128 v[210:213], v144 offset:20480
	ds_read_b128 v[214:217], v144 offset:21504
	ds_read_b128 v[218:221], v144 offset:22528
	ds_read_b128 v[222:225], v144 offset:23552
	global_load_lds_dwordx4 v96, s[82:83]
	s_add_i32 m0, s56, 0x2000
	s_add_u32 s56, s82, 0x20000
	v_lshl_add_u64 v[156:157], s[82:83], 0, v[130:131]
	s_addc_u32 s57, s83, 0
	s_add_i32 s58, s59, s75
	global_load_lds_dwordx4 v130, s[82:83]
	s_mov_b32 m0, s58
	v_lshl_add_u64 v[202:203], s[84:85], 0, v[132:133]
	global_load_lds_dwordx4 v96, s[56:57]
	s_add_i32 m0, s58, 0x2000
	s_nop 0
	global_load_lds_dwordx4 v130, s[56:57]
	v_lshl_add_u64 v[198:199], s[84:85], 0, v[134:135]
	s_mov_b32 m0, s10
	s_nop 0
	global_load_lds_dwordx4 v134, s[84:85]
	s_mov_b32 m0, s12
	s_nop 0
	global_load_lds_dwordx4 v132, s[84:85]
	v_cmp_ne_u32_e32 vcc, 0, v243
	s_cbranch_vccnz .Lrx_uq_1
	s_waitcnt vmcnt(8)
.Lrx_uq_1:
	s_waitcnt vmcnt(24)
	v_mov_b32_e32 v243, 0
	s_waitcnt lgkmcnt(0)
	s_setprio 1
	s_barrier
	v_mfma_f32_16x16x32_bf16 v[60:63], v[146:149], v[182:185], v[60:63]
	v_mfma_f32_16x16x32_bf16 v[56:59], v[158:161], v[182:185], v[56:59]
	v_mfma_f32_16x16x32_bf16 v[52:55], v[146:149], v[190:193], v[52:55]
	v_mfma_f32_16x16x32_bf16 v[48:51], v[158:161], v[190:193], v[48:51]
	v_mfma_f32_16x16x32_bf16 v[36:39], v[146:149], v[210:213], v[36:39]
	v_mfma_f32_16x16x32_bf16 v[32:35], v[158:161], v[210:213], v[32:35]
	v_mfma_f32_16x16x32_bf16 v[20:23], v[146:149], v[218:221], v[20:23]
	v_mfma_f32_16x16x32_bf16 v[16:19], v[158:161], v[218:221], v[16:19]
	v_mfma_f32_16x16x32_bf16 v[60:63], v[150:153], v[186:189], v[60:63]
	v_mfma_f32_16x16x32_bf16 v[56:59], v[162:165], v[186:189], v[56:59]
	v_mfma_f32_16x16x32_bf16 v[52:55], v[150:153], v[194:197], v[52:55]
	v_mfma_f32_16x16x32_bf16 v[48:51], v[162:165], v[194:197], v[48:51]
	v_mfma_f32_16x16x32_bf16 v[36:39], v[150:153], v[214:217], v[36:39]
	v_mfma_f32_16x16x32_bf16 v[32:35], v[162:165], v[214:217], v[32:35]
	v_mfma_f32_16x16x32_bf16 v[20:23], v[150:153], v[222:225], v[20:23]
	v_mfma_f32_16x16x32_bf16 v[16:19], v[162:165], v[222:225], v[16:19]
	v_mfma_f32_16x16x32_bf16 v[44:47], v[166:169], v[182:185], v[44:47]
	v_mfma_f32_16x16x32_bf16 v[40:43], v[174:177], v[182:185], v[40:43]
	v_mfma_f32_16x16x32_bf16 v[28:31], v[166:169], v[190:193], v[28:31]
	v_mfma_f32_16x16x32_bf16 v[24:27], v[174:177], v[190:193], v[24:27]
	v_mfma_f32_16x16x32_bf16 v[12:15], v[166:169], v[210:213], v[12:15]
	v_mfma_f32_16x16x32_bf16 v[8:11], v[174:177], v[210:213], v[8:11]
	v_mfma_f32_16x16x32_bf16 v[4:7], v[166:169], v[218:221], v[4:7]
	v_mfma_f32_16x16x32_bf16 v[0:3], v[174:177], v[218:221], v[0:3]
	v_mfma_f32_16x16x32_bf16 v[44:47], v[170:173], v[186:189], v[44:47]
	v_mfma_f32_16x16x32_bf16 v[40:43], v[178:181], v[186:189], v[40:43]
	v_mfma_f32_16x16x32_bf16 v[28:31], v[170:173], v[194:197], v[28:31]
	v_mfma_f32_16x16x32_bf16 v[24:27], v[178:181], v[194:197], v[24:27]
	v_mfma_f32_16x16x32_bf16 v[12:15], v[170:173], v[214:217], v[12:15]
	v_mfma_f32_16x16x32_bf16 v[8:11], v[178:181], v[214:217], v[8:11]
	v_mfma_f32_16x16x32_bf16 v[4:7], v[170:173], v[222:225], v[4:7]
	v_mfma_f32_16x16x32_bf16 v[0:3], v[178:181], v[222:225], v[0:3]
	s_barrier
	s_setprio 0
	s_add_i32 s58, 0, 0x18000
	v_add_u32_e32 v145, s58, v142
	s_add_i32 s59, 0, 0x1c000
	ds_read_b128 v[146:149], v145
	ds_read_b128 v[150:153], v145 offset:1024
	ds_read_b128 v[158:161], v145 offset:2048
	ds_read_b128 v[162:165], v145 offset:3072
	v_add_u32_e32 v145, s59, v142
	ds_read_b128 v[166:169], v145
	ds_read_b128 v[170:173], v145 offset:1024
	ds_read_b128 v[174:177], v145 offset:2048
	ds_read_b128 v[178:181], v145 offset:3072
	s_add_u32 s56, s84, 0x20000
	s_addc_u32 s57, s85, 0
	s_mov_b32 m0, s18
	ds_read_b128 v[182:185], v144 offset:32768
	ds_read_b128 v[186:189], v144 offset:33792
	ds_read_b128 v[190:193], v144 offset:34816
	ds_read_b128 v[194:197], v144 offset:35840
	ds_read_b128 v[210:213], v144 offset:36864
	ds_read_b128 v[214:217], v144 offset:37888
	ds_read_b128 v[218:221], v144 offset:38912
	ds_read_b128 v[222:225], v144 offset:39936
	global_load_lds_dwordx4 v134, s[56:57]
	s_mov_b32 m0, s20
	s_nop 0
	global_load_lds_dwordx4 v132, s[56:57]
	s_waitcnt vmcnt(8)
	s_waitcnt lgkmcnt(0)
	s_setprio 1
	s_barrier
	v_mfma_f32_16x16x32_bf16 v[126:129], v[146:149], v[182:185], v[126:129]
	v_mfma_f32_16x16x32_bf16 v[122:125], v[158:161], v[182:185], v[122:125]
	v_mfma_f32_16x16x32_bf16 v[118:121], v[146:149], v[190:193], v[118:121]
	v_mfma_f32_16x16x32_bf16 v[114:117], v[158:161], v[190:193], v[114:117]
	v_mfma_f32_16x16x32_bf16 v[102:105], v[146:149], v[210:213], v[102:105]
	v_mfma_f32_16x16x32_bf16 v[98:101], v[158:161], v[210:213], v[98:101]
	v_mfma_f32_16x16x32_bf16 v[84:87], v[146:149], v[218:221], v[84:87]
	v_mfma_f32_16x16x32_bf16 v[80:83], v[158:161], v[218:221], v[80:83]
	v_mfma_f32_16x16x32_bf16 v[126:129], v[150:153], v[186:189], v[126:129]
	v_mfma_f32_16x16x32_bf16 v[122:125], v[162:165], v[186:189], v[122:125]
	v_mfma_f32_16x16x32_bf16 v[118:121], v[150:153], v[194:197], v[118:121]
	v_mfma_f32_16x16x32_bf16 v[114:117], v[162:165], v[194:197], v[114:117]
	v_mfma_f32_16x16x32_bf16 v[102:105], v[150:153], v[214:217], v[102:105]
	v_mfma_f32_16x16x32_bf16 v[98:101], v[162:165], v[214:217], v[98:101]
	v_mfma_f32_16x16x32_bf16 v[84:87], v[150:153], v[222:225], v[84:87]
	v_mfma_f32_16x16x32_bf16 v[80:83], v[162:165], v[222:225], v[80:83]
	v_mfma_f32_16x16x32_bf16 v[110:113], v[166:169], v[182:185], v[110:113]
	v_mfma_f32_16x16x32_bf16 v[106:109], v[174:177], v[182:185], v[106:109]
	v_mfma_f32_16x16x32_bf16 v[92:95], v[166:169], v[190:193], v[92:95]
	v_mfma_f32_16x16x32_bf16 v[88:91], v[174:177], v[190:193], v[88:91]
	v_mfma_f32_16x16x32_bf16 v[76:79], v[166:169], v[210:213], v[76:79]
	v_mfma_f32_16x16x32_bf16 v[72:75], v[174:177], v[210:213], v[72:75]
	v_mfma_f32_16x16x32_bf16 v[68:71], v[166:169], v[218:221], v[68:71]
	v_mfma_f32_16x16x32_bf16 v[64:67], v[174:177], v[218:221], v[64:67]
	v_mfma_f32_16x16x32_bf16 v[110:113], v[170:173], v[186:189], v[110:113]
	v_mfma_f32_16x16x32_bf16 v[106:109], v[178:181], v[186:189], v[106:109]
	v_mfma_f32_16x16x32_bf16 v[92:95], v[170:173], v[194:197], v[92:95]
	v_mfma_f32_16x16x32_bf16 v[88:91], v[178:181], v[194:197], v[88:91]
	v_mfma_f32_16x16x32_bf16 v[76:79], v[170:173], v[214:217], v[76:79]
	v_mfma_f32_16x16x32_bf16 v[72:75], v[178:181], v[214:217], v[72:75]
	v_mfma_f32_16x16x32_bf16 v[68:71], v[170:173], v[222:225], v[68:71]
	v_mfma_f32_16x16x32_bf16 v[64:67], v[178:181], v[222:225], v[64:67]
	s_barrier
	s_setprio 0
	s_add_i32 s56, s58, s75
	v_lshl_add_u64 v[154:155], v[154:155], 0, s[64:65]
	s_mov_b32 m0, s56
	ds_read_b128 v[182:185], v144 offset:49152
	ds_read_b128 v[186:189], v144 offset:50176
	ds_read_b128 v[190:193], v144 offset:51200
	ds_read_b128 v[194:197], v144 offset:52224
	ds_read_b128 v[210:213], v144 offset:53248
	ds_read_b128 v[214:217], v144 offset:54272
	ds_read_b128 v[218:221], v144 offset:55296
	ds_read_b128 v[222:225], v144 offset:56320
	global_load_lds_dwordx4 v[154:155], off
	s_add_i32 m0, s56, 0x2000
	s_add_u32 s56, s82, 0x20080
	v_lshl_add_u64 v[154:155], v[156:157], 0, s[64:65]
	s_addc_u32 s57, s83, 0
	s_add_i32 s58, s59, s75
	global_load_lds_dwordx4 v[154:155], off
	s_mov_b32 m0, s58
	s_nop 0
	global_load_lds_dwordx4 v96, s[56:57]
	s_add_i32 m0, s58, 0x2000
	s_nop 0
	global_load_lds_dwordx4 v130, s[56:57]
	v_lshl_add_u64 v[154:155], v[198:199], 0, s[64:65]
	s_mov_b32 m0, s26
	s_nop 0
	global_load_lds_dwordx4 v[154:155], off
	v_lshl_add_u64 v[154:155], v[202:203], 0, s[64:65]
	s_mov_b32 m0, s27
	s_nop 0
	global_load_lds_dwordx4 v[154:155], off
	s_waitcnt vmcnt(8)
	s_waitcnt lgkmcnt(0)
	s_setprio 1
	s_barrier
	v_mfma_f32_16x16x32_bf16 v[60:63], v[146:149], v[182:185], v[60:63]
	v_mfma_f32_16x16x32_bf16 v[56:59], v[158:161], v[182:185], v[56:59]
	v_mfma_f32_16x16x32_bf16 v[52:55], v[146:149], v[190:193], v[52:55]
	v_mfma_f32_16x16x32_bf16 v[48:51], v[158:161], v[190:193], v[48:51]
	v_mfma_f32_16x16x32_bf16 v[36:39], v[146:149], v[210:213], v[36:39]
	v_mfma_f32_16x16x32_bf16 v[32:35], v[158:161], v[210:213], v[32:35]
	v_mfma_f32_16x16x32_bf16 v[20:23], v[146:149], v[218:221], v[20:23]
	v_mfma_f32_16x16x32_bf16 v[16:19], v[158:161], v[218:221], v[16:19]
	v_mfma_f32_16x16x32_bf16 v[60:63], v[150:153], v[186:189], v[60:63]
	v_mfma_f32_16x16x32_bf16 v[56:59], v[162:165], v[186:189], v[56:59]
	v_mfma_f32_16x16x32_bf16 v[52:55], v[150:153], v[194:197], v[52:55]
	v_mfma_f32_16x16x32_bf16 v[48:51], v[162:165], v[194:197], v[48:51]
	v_mfma_f32_16x16x32_bf16 v[36:39], v[150:153], v[214:217], v[36:39]
	v_mfma_f32_16x16x32_bf16 v[32:35], v[162:165], v[214:217], v[32:35]
	v_mfma_f32_16x16x32_bf16 v[20:23], v[150:153], v[222:225], v[20:23]
	v_mfma_f32_16x16x32_bf16 v[16:19], v[162:165], v[222:225], v[16:19]
	v_mfma_f32_16x16x32_bf16 v[44:47], v[166:169], v[182:185], v[44:47]
	v_mfma_f32_16x16x32_bf16 v[40:43], v[174:177], v[182:185], v[40:43]
	v_mfma_f32_16x16x32_bf16 v[28:31], v[166:169], v[190:193], v[28:31]
	v_mfma_f32_16x16x32_bf16 v[24:27], v[174:177], v[190:193], v[24:27]
	v_mfma_f32_16x16x32_bf16 v[12:15], v[166:169], v[210:213], v[12:15]
	v_mfma_f32_16x16x32_bf16 v[8:11], v[174:177], v[210:213], v[8:11]
	v_mfma_f32_16x16x32_bf16 v[4:7], v[166:169], v[218:221], v[4:7]
	v_mfma_f32_16x16x32_bf16 v[0:3], v[174:177], v[218:221], v[0:3]
	v_mfma_f32_16x16x32_bf16 v[44:47], v[170:173], v[186:189], v[44:47]
	v_mfma_f32_16x16x32_bf16 v[40:43], v[178:181], v[186:189], v[40:43]
	v_mfma_f32_16x16x32_bf16 v[28:31], v[170:173], v[194:197], v[28:31]
	v_mfma_f32_16x16x32_bf16 v[24:27], v[178:181], v[194:197], v[24:27]
	v_mfma_f32_16x16x32_bf16 v[12:15], v[170:173], v[214:217], v[12:15]
	v_mfma_f32_16x16x32_bf16 v[8:11], v[178:181], v[214:217], v[8:11]
	v_mfma_f32_16x16x32_bf16 v[4:7], v[170:173], v[222:225], v[4:7]
	v_mfma_f32_16x16x32_bf16 v[0:3], v[178:181], v[222:225], v[0:3]
	s_barrier
	s_setprio 0
	s_add_i32 s55, s55, 2
	s_add_u32 s68, s68, 0x100
	s_addc_u32 s69, s69, 0
	s_add_u32 s51, s51, 0x100
	s_addc_u32 s54, s54, 0
	s_cmp_gt_u32 s55, 5
	s_cbranch_scc0 .LBB0_636
	v_mov_b32_e32 v243, 1
	v_readlane_b32 s6, v251, 54
	v_readlane_b32 s7, v251, 55
	s_and_b64 vcc, exec, s[6:7]
	s_cbranch_vccz .LBB0_639
	s_barrier

.LBB0_656:
	s_add_u32 s58, s68, 0xfffe0080
	s_addc_u32 s59, s69, -1
	s_add_i32 s61, 0, 0x10000
	s_cmp_eq_u32 s57, 4
	s_cselect_b32 s85, s43, s59
	s_cselect_b32 s84, s51, s58
	v_add_u32_e32 v145, s61, v142
	s_cselect_b32 s83, s31, s56
	s_cselect_b32 s82, s54, s55
	s_add_i32 s62, 0, 0x14000
	ds_read_b128 v[146:149], v145
	ds_read_b128 v[150:153], v145 offset:1024
	ds_read_b128 v[158:161], v145 offset:2048
	ds_read_b128 v[162:165], v145 offset:3072
	v_add_u32_e32 v145, s62, v142
	ds_read_b128 v[166:169], v145
	ds_read_b128 v[170:173], v145 offset:1024
	ds_read_b128 v[174:177], v145 offset:2048
	ds_read_b128 v[178:181], v145 offset:3072
	s_add_i32 m0, s18, 0xc000
	ds_read_b128 v[182:185], v144
	ds_read_b128 v[186:189], v144 offset:1024
	ds_read_b128 v[190:193], v144 offset:2048
	ds_read_b128 v[194:197], v144 offset:3072
	ds_read_b128 v[210:213], v144 offset:4096
	ds_read_b128 v[214:217], v144 offset:5120
	ds_read_b128 v[218:221], v144 offset:6144
	ds_read_b128 v[222:225], v144 offset:7168
	global_load_lds_dwordx4 v136, s[68:69]
	s_add_i32 m0, s18, 0xe000
	s_nop 0
	global_load_lds_dwordx4 v138, s[68:69]
	v_cmp_ne_u32_e32 vcc, 0, v243
	s_cbranch_vccnz .Lrx_ukv_0
	s_waitcnt vmcnt(8)
.Lrx_ukv_0:
	s_waitcnt vmcnt(24)
	s_waitcnt lgkmcnt(0)
	s_setprio 1
	s_barrier
	v_mfma_f32_16x16x32_bf16 v[126:129], v[146:149], v[182:185], v[126:129]
	v_mfma_f32_16x16x32_bf16 v[122:125], v[158:161], v[182:185], v[122:125]
	v_mfma_f32_16x16x32_bf16 v[118:121], v[146:149], v[190:193], v[118:121]
	v_mfma_f32_16x16x32_bf16 v[114:117], v[158:161], v[190:193], v[114:117]
	v_mfma_f32_16x16x32_bf16 v[102:105], v[146:149], v[210:213], v[102:105]
	v_mfma_f32_16x16x32_bf16 v[98:101], v[158:161], v[210:213], v[98:101]
	v_mfma_f32_16x16x32_bf16 v[84:87], v[146:149], v[218:221], v[84:87]
	v_mfma_f32_16x16x32_bf16 v[80:83], v[158:161], v[218:221], v[80:83]
	v_mfma_f32_16x16x32_bf16 v[126:129], v[150:153], v[186:189], v[126:129]
	v_mfma_f32_16x16x32_bf16 v[122:125], v[162:165], v[186:189], v[122:125]
	v_mfma_f32_16x16x32_bf16 v[118:121], v[150:153], v[194:197], v[118:121]
	v_mfma_f32_16x16x32_bf16 v[114:117], v[162:165], v[194:197], v[114:117]
	v_mfma_f32_16x16x32_bf16 v[102:105], v[150:153], v[214:217], v[102:105]
	v_mfma_f32_16x16x32_bf16 v[98:101], v[162:165], v[214:217], v[98:101]
	v_mfma_f32_16x16x32_bf16 v[84:87], v[150:153], v[222:225], v[84:87]
	v_mfma_f32_16x16x32_bf16 v[80:83], v[162:165], v[222:225], v[80:83]
	v_mfma_f32_16x16x32_bf16 v[110:113], v[166:169], v[182:185], v[110:113]
	v_mfma_f32_16x16x32_bf16 v[106:109], v[174:177], v[182:185], v[106:109]
	v_mfma_f32_16x16x32_bf16 v[92:95], v[166:169], v[190:193], v[92:95]
	v_mfma_f32_16x16x32_bf16 v[88:91], v[174:177], v[190:193], v[88:91]
	v_mfma_f32_16x16x32_bf16 v[76:79], v[166:169], v[210:213], v[76:79]
	v_mfma_f32_16x16x32_bf16 v[72:75], v[174:177], v[210:213], v[72:75]
	v_mfma_f32_16x16x32_bf16 v[68:71], v[166:169], v[218:221], v[68:71]
	v_mfma_f32_16x16x32_bf16 v[64:67], v[174:177], v[218:221], v[64:67]
	v_mfma_f32_16x16x32_bf16 v[110:113], v[170:173], v[186:189], v[110:113]
	v_mfma_f32_16x16x32_bf16 v[106:109], v[178:181], v[186:189], v[106:109]
	v_mfma_f32_16x16x32_bf16 v[92:95], v[170:173], v[194:197], v[92:95]
	v_mfma_f32_16x16x32_bf16 v[88:91], v[178:181], v[194:197], v[88:91]
	v_mfma_f32_16x16x32_bf16 v[76:79], v[170:173], v[214:217], v[76:79]
	v_mfma_f32_16x16x32_bf16 v[72:75], v[178:181], v[214:217], v[72:75]
	v_mfma_f32_16x16x32_bf16 v[68:71], v[170:173], v[222:225], v[68:71]
	v_mfma_f32_16x16x32_bf16 v[64:67], v[178:181], v[222:225], v[64:67]
	s_barrier
	s_setprio 0
	s_add_i32 s58, s61, s75
	v_lshl_add_u64 v[154:155], s[82:83], 0, v[96:97]
	s_mov_b32 m0, s58
	ds_read_b128 v[182:185], v144 offset:16384
	ds_read_b128 v[186:189], v144 offset:17408
	ds_read_b128 v[190:193], v144 offset:18432
	ds_read_b128 v[194:197], v144 offset:19456
	ds_read_b128 v[210:213], v144 offset:20480
	ds_read_b128 v[214:217], v144 offset:21504
	ds_read_b128 v[218:221], v144 offset:22528
	ds_read_b128 v[222:225], v144 offset:23552
	global_load_lds_dwordx4 v96, s[82:83]
	s_add_i32 m0, s58, 0x2000
	s_add_u32 s58, s82, 0x20000
	v_lshl_add_u64 v[156:157], s[82:83], 0, v[130:131]
	s_addc_u32 s59, s83, 0
	s_add_i32 s61, s62, s75
	global_load_lds_dwordx4 v130, s[82:83]
	s_mov_b32 m0, s61
	v_lshl_add_u64 v[202:203], s[84:85], 0, v[132:133]
	global_load_lds_dwordx4 v96, s[58:59]
	s_add_i32 m0, s61, 0x2000
	s_nop 0
	global_load_lds_dwordx4 v130, s[58:59]
	v_lshl_add_u64 v[198:199], s[84:85], 0, v[134:135]
	s_mov_b32 m0, s18
	s_nop 0
	global_load_lds_dwordx4 v134, s[84:85]
	s_mov_b32 m0, s20
	s_nop 0
	global_load_lds_dwordx4 v132, s[84:85]
	v_cmp_ne_u32_e32 vcc, 0, v243
	s_cbranch_vccnz .Lrx_ukv_1
	s_waitcnt vmcnt(8)
.Lrx_ukv_1:
	s_waitcnt vmcnt(24)
	v_mov_b32_e32 v243, 0
	s_waitcnt lgkmcnt(0)
	s_setprio 1
	s_barrier
	v_mfma_f32_16x16x32_bf16 v[60:63], v[146:149], v[182:185], v[60:63]
	v_mfma_f32_16x16x32_bf16 v[56:59], v[158:161], v[182:185], v[56:59]
	v_mfma_f32_16x16x32_bf16 v[52:55], v[146:149], v[190:193], v[52:55]
	v_mfma_f32_16x16x32_bf16 v[48:51], v[158:161], v[190:193], v[48:51]
	v_mfma_f32_16x16x32_bf16 v[36:39], v[146:149], v[210:213], v[36:39]
	v_mfma_f32_16x16x32_bf16 v[32:35], v[158:161], v[210:213], v[32:35]
	v_mfma_f32_16x16x32_bf16 v[20:23], v[146:149], v[218:221], v[20:23]
	v_mfma_f32_16x16x32_bf16 v[16:19], v[158:161], v[218:221], v[16:19]
	v_mfma_f32_16x16x32_bf16 v[60:63], v[150:153], v[186:189], v[60:63]
	v_mfma_f32_16x16x32_bf16 v[56:59], v[162:165], v[186:189], v[56:59]
	v_mfma_f32_16x16x32_bf16 v[52:55], v[150:153], v[194:197], v[52:55]
	v_mfma_f32_16x16x32_bf16 v[48:51], v[162:165], v[194:197], v[48:51]
	v_mfma_f32_16x16x32_bf16 v[36:39], v[150:153], v[214:217], v[36:39]
	v_mfma_f32_16x16x32_bf16 v[32:35], v[162:165], v[214:217], v[32:35]
	v_mfma_f32_16x16x32_bf16 v[20:23], v[150:153], v[222:225], v[20:23]
	v_mfma_f32_16x16x32_bf16 v[16:19], v[162:165], v[222:225], v[16:19]
	v_mfma_f32_16x16x32_bf16 v[44:47], v[166:169], v[182:185], v[44:47]
	v_mfma_f32_16x16x32_bf16 v[40:43], v[174:177], v[182:185], v[40:43]
	v_mfma_f32_16x16x32_bf16 v[28:31], v[166:169], v[190:193], v[28:31]
	v_mfma_f32_16x16x32_bf16 v[24:27], v[174:177], v[190:193], v[24:27]
	v_mfma_f32_16x16x32_bf16 v[12:15], v[166:169], v[210:213], v[12:15]
	v_mfma_f32_16x16x32_bf16 v[8:11], v[174:177], v[210:213], v[8:11]
	v_mfma_f32_16x16x32_bf16 v[4:7], v[166:169], v[218:221], v[4:7]
	v_mfma_f32_16x16x32_bf16 v[0:3], v[174:177], v[218:221], v[0:3]
	v_mfma_f32_16x16x32_bf16 v[44:47], v[170:173], v[186:189], v[44:47]
	v_mfma_f32_16x16x32_bf16 v[40:43], v[178:181], v[186:189], v[40:43]
	v_mfma_f32_16x16x32_bf16 v[28:31], v[170:173], v[194:197], v[28:31]
	v_mfma_f32_16x16x32_bf16 v[24:27], v[178:181], v[194:197], v[24:27]
	v_mfma_f32_16x16x32_bf16 v[12:15], v[170:173], v[214:217], v[12:15]
	v_mfma_f32_16x16x32_bf16 v[8:11], v[178:181], v[214:217], v[8:11]
	v_mfma_f32_16x16x32_bf16 v[4:7], v[170:173], v[222:225], v[4:7]
	v_mfma_f32_16x16x32_bf16 v[0:3], v[178:181], v[222:225], v[0:3]
	s_barrier
	s_setprio 0
	s_add_i32 s61, 0, 0x18000
	v_add_u32_e32 v145, s61, v142
	s_add_i32 s62, 0, 0x1c000
	ds_read_b128 v[146:149], v145
	ds_read_b128 v[150:153], v145 offset:1024
	ds_read_b128 v[158:161], v145 offset:2048
	ds_read_b128 v[162:165], v145 offset:3072
	v_add_u32_e32 v145, s62, v142
	ds_read_b128 v[166:169], v145
	ds_read_b128 v[170:173], v145 offset:1024
	ds_read_b128 v[174:177], v145 offset:2048
	ds_read_b128 v[178:181], v145 offset:3072
	s_add_u32 s58, s84, 0x20000
	s_addc_u32 s59, s85, 0
	s_mov_b32 m0, s26
	ds_read_b128 v[182:185], v144 offset:32768
	ds_read_b128 v[186:189], v144 offset:33792
	ds_read_b128 v[190:193], v144 offset:34816
	ds_read_b128 v[194:197], v144 offset:35840
	ds_read_b128 v[210:213], v144 offset:36864
	ds_read_b128 v[214:217], v144 offset:37888
	ds_read_b128 v[218:221], v144 offset:38912
	ds_read_b128 v[222:225], v144 offset:39936
	global_load_lds_dwordx4 v134, s[58:59]
	s_mov_b32 m0, s27
	s_nop 0
	global_load_lds_dwordx4 v132, s[58:59]
	s_waitcnt vmcnt(8)
	s_waitcnt lgkmcnt(0)
	s_setprio 1
	s_barrier
	v_mfma_f32_16x16x32_bf16 v[126:129], v[146:149], v[182:185], v[126:129]
	v_mfma_f32_16x16x32_bf16 v[122:125], v[158:161], v[182:185], v[122:125]
	v_mfma_f32_16x16x32_bf16 v[118:121], v[146:149], v[190:193], v[118:121]
	v_mfma_f32_16x16x32_bf16 v[114:117], v[158:161], v[190:193], v[114:117]
	v_mfma_f32_16x16x32_bf16 v[102:105], v[146:149], v[210:213], v[102:105]
	v_mfma_f32_16x16x32_bf16 v[98:101], v[158:161], v[210:213], v[98:101]
	v_mfma_f32_16x16x32_bf16 v[84:87], v[146:149], v[218:221], v[84:87]
	v_mfma_f32_16x16x32_bf16 v[80:83], v[158:161], v[218:221], v[80:83]
	v_mfma_f32_16x16x32_bf16 v[126:129], v[150:153], v[186:189], v[126:129]
	v_mfma_f32_16x16x32_bf16 v[122:125], v[162:165], v[186:189], v[122:125]
	v_mfma_f32_16x16x32_bf16 v[118:121], v[150:153], v[194:197], v[118:121]
	v_mfma_f32_16x16x32_bf16 v[114:117], v[162:165], v[194:197], v[114:117]
	v_mfma_f32_16x16x32_bf16 v[102:105], v[150:153], v[214:217], v[102:105]
	v_mfma_f32_16x16x32_bf16 v[98:101], v[162:165], v[214:217], v[98:101]
	v_mfma_f32_16x16x32_bf16 v[84:87], v[150:153], v[222:225], v[84:87]
	v_mfma_f32_16x16x32_bf16 v[80:83], v[162:165], v[222:225], v[80:83]
	v_mfma_f32_16x16x32_bf16 v[110:113], v[166:169], v[182:185], v[110:113]
	v_mfma_f32_16x16x32_bf16 v[106:109], v[174:177], v[182:185], v[106:109]
	v_mfma_f32_16x16x32_bf16 v[92:95], v[166:169], v[190:193], v[92:95]
	v_mfma_f32_16x16x32_bf16 v[88:91], v[174:177], v[190:193], v[88:91]
	v_mfma_f32_16x16x32_bf16 v[76:79], v[166:169], v[210:213], v[76:79]
	v_mfma_f32_16x16x32_bf16 v[72:75], v[174:177], v[210:213], v[72:75]
	v_mfma_f32_16x16x32_bf16 v[68:71], v[166:169], v[218:221], v[68:71]
	v_mfma_f32_16x16x32_bf16 v[64:67], v[174:177], v[218:221], v[64:67]
	v_mfma_f32_16x16x32_bf16 v[110:113], v[170:173], v[186:189], v[110:113]
	v_mfma_f32_16x16x32_bf16 v[106:109], v[178:181], v[186:189], v[106:109]
	v_mfma_f32_16x16x32_bf16 v[92:95], v[170:173], v[194:197], v[92:95]
	v_mfma_f32_16x16x32_bf16 v[88:91], v[178:181], v[194:197], v[88:91]
	v_mfma_f32_16x16x32_bf16 v[76:79], v[170:173], v[214:217], v[76:79]
	v_mfma_f32_16x16x32_bf16 v[72:75], v[178:181], v[214:217], v[72:75]
	v_mfma_f32_16x16x32_bf16 v[68:71], v[170:173], v[222:225], v[68:71]
	v_mfma_f32_16x16x32_bf16 v[64:67], v[178:181], v[222:225], v[64:67]
	s_barrier
	s_setprio 0
	s_add_i32 s58, s61, s75
	v_lshl_add_u64 v[154:155], v[154:155], 0, s[64:65]
	s_mov_b32 m0, s58
	ds_read_b128 v[182:185], v144 offset:49152
	ds_read_b128 v[186:189], v144 offset:50176
	ds_read_b128 v[190:193], v144 offset:51200
	ds_read_b128 v[194:197], v144 offset:52224
	ds_read_b128 v[210:213], v144 offset:53248
	ds_read_b128 v[214:217], v144 offset:54272
	ds_read_b128 v[218:221], v144 offset:55296
	ds_read_b128 v[222:225], v144 offset:56320
	global_load_lds_dwordx4 v[154:155], off
	s_add_i32 m0, s58, 0x2000
	s_add_u32 s58, s82, 0x20080
	v_lshl_add_u64 v[154:155], v[156:157], 0, s[64:65]
	s_addc_u32 s59, s83, 0
	s_add_i32 s61, s62, s75
	global_load_lds_dwordx4 v[154:155], off
	s_mov_b32 m0, s61
	s_nop 0
	global_load_lds_dwordx4 v96, s[58:59]
	s_add_i32 m0, s61, 0x2000
	s_nop 0
	global_load_lds_dwordx4 v130, s[58:59]
	v_lshl_add_u64 v[154:155], v[198:199], 0, s[64:65]
	s_mov_b32 m0, s28
	s_nop 0
	global_load_lds_dwordx4 v[154:155], off
	v_lshl_add_u64 v[154:155], v[202:203], 0, s[64:65]
	s_mov_b32 m0, s33
	s_nop 0
	global_load_lds_dwordx4 v[154:155], off
	s_waitcnt vmcnt(8)
	s_waitcnt lgkmcnt(0)
	s_setprio 1
	s_barrier
	v_mfma_f32_16x16x32_bf16 v[60:63], v[146:149], v[182:185], v[60:63]
	v_mfma_f32_16x16x32_bf16 v[56:59], v[158:161], v[182:185], v[56:59]
	v_mfma_f32_16x16x32_bf16 v[52:55], v[146:149], v[190:193], v[52:55]
	v_mfma_f32_16x16x32_bf16 v[48:51], v[158:161], v[190:193], v[48:51]
	v_mfma_f32_16x16x32_bf16 v[36:39], v[146:149], v[210:213], v[36:39]
	v_mfma_f32_16x16x32_bf16 v[32:35], v[158:161], v[210:213], v[32:35]
	v_mfma_f32_16x16x32_bf16 v[20:23], v[146:149], v[218:221], v[20:23]
	v_mfma_f32_16x16x32_bf16 v[16:19], v[158:161], v[218:221], v[16:19]
	v_mfma_f32_16x16x32_bf16 v[60:63], v[150:153], v[186:189], v[60:63]
	v_mfma_f32_16x16x32_bf16 v[56:59], v[162:165], v[186:189], v[56:59]
	v_mfma_f32_16x16x32_bf16 v[52:55], v[150:153], v[194:197], v[52:55]
	v_mfma_f32_16x16x32_bf16 v[48:51], v[162:165], v[194:197], v[48:51]
	v_mfma_f32_16x16x32_bf16 v[36:39], v[150:153], v[214:217], v[36:39]
	v_mfma_f32_16x16x32_bf16 v[32:35], v[162:165], v[214:217], v[32:35]
	v_mfma_f32_16x16x32_bf16 v[20:23], v[150:153], v[222:225], v[20:23]
	v_mfma_f32_16x16x32_bf16 v[16:19], v[162:165], v[222:225], v[16:19]
	v_mfma_f32_16x16x32_bf16 v[44:47], v[166:169], v[182:185], v[44:47]
	v_mfma_f32_16x16x32_bf16 v[40:43], v[174:177], v[182:185], v[40:43]
	v_mfma_f32_16x16x32_bf16 v[28:31], v[166:169], v[190:193], v[28:31]
	v_mfma_f32_16x16x32_bf16 v[24:27], v[174:177], v[190:193], v[24:27]
	v_mfma_f32_16x16x32_bf16 v[12:15], v[166:169], v[210:213], v[12:15]
	v_mfma_f32_16x16x32_bf16 v[8:11], v[174:177], v[210:213], v[8:11]
	v_mfma_f32_16x16x32_bf16 v[4:7], v[166:169], v[218:221], v[4:7]
	v_mfma_f32_16x16x32_bf16 v[0:3], v[174:177], v[218:221], v[0:3]
	v_mfma_f32_16x16x32_bf16 v[44:47], v[170:173], v[186:189], v[44:47]
	v_mfma_f32_16x16x32_bf16 v[40:43], v[178:181], v[186:189], v[40:43]
	v_mfma_f32_16x16x32_bf16 v[28:31], v[170:173], v[194:197], v[28:31]
	v_mfma_f32_16x16x32_bf16 v[24:27], v[178:181], v[194:197], v[24:27]
	v_mfma_f32_16x16x32_bf16 v[12:15], v[170:173], v[214:217], v[12:15]
	v_mfma_f32_16x16x32_bf16 v[8:11], v[178:181], v[214:217], v[8:11]
	v_mfma_f32_16x16x32_bf16 v[4:7], v[170:173], v[222:225], v[4:7]
	v_mfma_f32_16x16x32_bf16 v[0:3], v[178:181], v[222:225], v[0:3]
	s_barrier
	s_setprio 0
	s_add_i32 s57, s57, 2
	s_add_u32 s68, s68, 0x100
	s_addc_u32 s69, s69, 0
	s_add_u32 s55, s55, 0x100
	s_addc_u32 s56, s56, 0
	s_cmp_gt_u32 s57, 5
	s_cbranch_scc0 .LBB0_656
	v_mov_b32_e32 v243, 1
	v_readlane_b32 s6, v251, 54
	v_readlane_b32 s7, v251, 55
	s_and_b64 vcc, exec, s[6:7]
	s_cbranch_vccz .LBB0_659
	s_barrier

.LBB0_1038:
	s_add_u32 s34, s44, 0xfff80080
	s_addc_u32 s35, s45, -1
	s_add_i32 s38, 0, 0x10000
	s_cmp_eq_u32 s33, 28
	s_cselect_b32 s87, s10, s35
	s_cselect_b32 s86, s12, s34
	s_cselect_b32 s85, s18, s31
	s_cselect_b32 s84, s20, s28
	s_add_i32 s39, 0, 0x14000
	v_add_u32_e32 v156, s38, v169
	v_add_u32_e32 v164, s39, v169
	ds_read_b128 v[130:133], v156
	ds_read_b128 v[134:137], v156 offset:1024
	ds_read_b128 v[152:155], v156 offset:2048
	ds_read_b128 v[156:159], v156 offset:3072
	ds_read_b128 v[160:163], v164
	ds_read_b128 v[172:175], v164 offset:1024
	ds_read_b128 v[176:179], v164 offset:2048
	ds_read_b128 v[180:183], v164 offset:3072
	s_add_i32 m0, s58, 0xc000
	ds_read_b128 v[184:187], v171
	ds_read_b128 v[188:191], v171 offset:1024
	ds_read_b128 v[192:195], v171 offset:2048
	ds_read_b128 v[196:199], v171 offset:3072
	ds_read_b128 v[202:205], v171 offset:4096
	ds_read_b128 v[210:213], v171 offset:5120
	ds_read_b128 v[214:217], v171 offset:6144
	ds_read_b128 v[218:221], v171 offset:7168
	global_load_lds_dwordx4 v148, s[44:45]
	s_add_i32 m0, s58, 0xe000
	s_nop 0
	global_load_lds_dwordx4 v150, s[44:45]
	v_cmp_ne_u32_e32 vcc, 0, v243
	s_cbranch_vccnz .Lrx_G_OUT_0
	s_waitcnt vmcnt(8)
.Lrx_G_OUT_0:
	s_waitcnt vmcnt(44)
	s_waitcnt lgkmcnt(0)
	s_setprio 1
	s_barrier
	v_mfma_f32_16x16x32_bf16 v[126:129], v[130:133], v[184:187], v[126:129]
	v_mfma_f32_16x16x32_bf16 v[122:125], v[152:155], v[184:187], v[122:125]
	v_mfma_f32_16x16x32_bf16 v[110:113], v[130:133], v[192:195], v[110:113]
	v_mfma_f32_16x16x32_bf16 v[106:109], v[152:155], v[192:195], v[106:109]
	v_mfma_f32_16x16x32_bf16 v[92:95], v[130:133], v[202:205], v[92:95]
	v_mfma_f32_16x16x32_bf16 v[88:91], v[152:155], v[202:205], v[88:91]
	v_mfma_f32_16x16x32_bf16 v[76:79], v[130:133], v[214:217], v[76:79]
	v_mfma_f32_16x16x32_bf16 v[72:75], v[152:155], v[214:217], v[72:75]
	v_mfma_f32_16x16x32_bf16 v[126:129], v[134:137], v[188:191], v[126:129]
	v_mfma_f32_16x16x32_bf16 v[122:125], v[156:159], v[188:191], v[122:125]
	v_mfma_f32_16x16x32_bf16 v[110:113], v[134:137], v[196:199], v[110:113]
	v_mfma_f32_16x16x32_bf16 v[106:109], v[156:159], v[196:199], v[106:109]
	v_mfma_f32_16x16x32_bf16 v[92:95], v[134:137], v[210:213], v[92:95]
	v_mfma_f32_16x16x32_bf16 v[88:91], v[156:159], v[210:213], v[88:91]
	v_mfma_f32_16x16x32_bf16 v[76:79], v[134:137], v[218:221], v[76:79]
	v_mfma_f32_16x16x32_bf16 v[72:75], v[156:159], v[218:221], v[72:75]
	v_mfma_f32_16x16x32_bf16 v[118:121], v[160:163], v[184:187], v[118:121]
	v_mfma_f32_16x16x32_bf16 v[114:117], v[176:179], v[184:187], v[114:117]
	v_mfma_f32_16x16x32_bf16 v[102:105], v[160:163], v[192:195], v[102:105]
	v_mfma_f32_16x16x32_bf16 v[98:101], v[176:179], v[192:195], v[98:101]
	v_mfma_f32_16x16x32_bf16 v[84:87], v[160:163], v[202:205], v[84:87]
	v_mfma_f32_16x16x32_bf16 v[80:83], v[176:179], v[202:205], v[80:83]
	v_mfma_f32_16x16x32_bf16 v[68:71], v[160:163], v[214:217], v[68:71]
	v_mfma_f32_16x16x32_bf16 v[64:67], v[176:179], v[214:217], v[64:67]
	v_mfma_f32_16x16x32_bf16 v[118:121], v[172:175], v[188:191], v[118:121]
	v_mfma_f32_16x16x32_bf16 v[114:117], v[180:183], v[188:191], v[114:117]
	v_mfma_f32_16x16x32_bf16 v[102:105], v[172:175], v[196:199], v[102:105]
	v_mfma_f32_16x16x32_bf16 v[98:101], v[180:183], v[196:199], v[98:101]
	v_mfma_f32_16x16x32_bf16 v[84:87], v[172:175], v[210:213], v[84:87]
	v_mfma_f32_16x16x32_bf16 v[80:83], v[180:183], v[210:213], v[80:83]
	v_mfma_f32_16x16x32_bf16 v[68:71], v[172:175], v[218:221], v[68:71]
	v_mfma_f32_16x16x32_bf16 v[64:67], v[180:183], v[218:221], v[64:67]
	s_barrier
	s_setprio 0
	s_add_i32 s34, s38, s75
	v_lshl_add_u64 v[164:165], s[84:85], 0, v[96:97]
	s_mov_b32 m0, s34
	ds_read_b128 v[184:187], v171 offset:16384
	ds_read_b128 v[188:191], v171 offset:17408
	ds_read_b128 v[192:195], v171 offset:18432
	ds_read_b128 v[196:199], v171 offset:19456
	ds_read_b128 v[202:205], v171 offset:20480
	ds_read_b128 v[210:213], v171 offset:21504
	ds_read_b128 v[214:217], v171 offset:22528
	ds_read_b128 v[218:221], v171 offset:23552
	global_load_lds_dwordx4 v96, s[84:85]
	s_add_i32 m0, s34, 0x2000
	s_add_u32 s34, s84, 0x80000
	v_lshl_add_u64 v[222:223], s[84:85], 0, v[142:143]
	s_addc_u32 s35, s85, 0
	s_add_i32 s38, s39, s75
	global_load_lds_dwordx4 v142, s[84:85]
	s_mov_b32 m0, s38
	v_lshl_add_u64 v[226:227], s[86:87], 0, v[144:145]
	global_load_lds_dwordx4 v96, s[34:35]
	s_add_i32 m0, s38, 0x2000
	s_nop 0
	global_load_lds_dwordx4 v142, s[34:35]
	v_lshl_add_u64 v[224:225], s[86:87], 0, v[146:147]
	s_mov_b32 m0, s58
	s_nop 0
	global_load_lds_dwordx4 v146, s[86:87]
	s_mov_b32 m0, s59
	s_nop 0
	global_load_lds_dwordx4 v144, s[86:87]
	v_cmp_ne_u32_e32 vcc, 0, v243
	s_cbranch_vccnz .Lrx_G_OUT_1
	s_waitcnt vmcnt(8)
.Lrx_G_OUT_1:
	s_waitcnt vmcnt(44)
	v_mov_b32_e32 v243, 0
	s_waitcnt lgkmcnt(0)
	s_setprio 1
	s_barrier
	v_mfma_f32_16x16x32_bf16 v[60:63], v[130:133], v[184:187], v[60:63]
	v_mfma_f32_16x16x32_bf16 v[56:59], v[152:155], v[184:187], v[56:59]
	v_mfma_f32_16x16x32_bf16 v[44:47], v[130:133], v[192:195], v[44:47]
	v_mfma_f32_16x16x32_bf16 v[40:43], v[152:155], v[192:195], v[40:43]
	v_mfma_f32_16x16x32_bf16 v[28:31], v[130:133], v[202:205], v[28:31]
	v_mfma_f32_16x16x32_bf16 v[24:27], v[152:155], v[202:205], v[24:27]
	v_mfma_f32_16x16x32_bf16 v[12:15], v[130:133], v[214:217], v[12:15]
	v_mfma_f32_16x16x32_bf16 v[8:11], v[152:155], v[214:217], v[8:11]
	v_mfma_f32_16x16x32_bf16 v[60:63], v[134:137], v[188:191], v[60:63]
	v_mfma_f32_16x16x32_bf16 v[56:59], v[156:159], v[188:191], v[56:59]
	v_mfma_f32_16x16x32_bf16 v[44:47], v[134:137], v[196:199], v[44:47]
	v_mfma_f32_16x16x32_bf16 v[40:43], v[156:159], v[196:199], v[40:43]
	v_mfma_f32_16x16x32_bf16 v[28:31], v[134:137], v[210:213], v[28:31]
	v_mfma_f32_16x16x32_bf16 v[24:27], v[156:159], v[210:213], v[24:27]
	v_mfma_f32_16x16x32_bf16 v[12:15], v[134:137], v[218:221], v[12:15]
	v_mfma_f32_16x16x32_bf16 v[8:11], v[156:159], v[218:221], v[8:11]
	v_mfma_f32_16x16x32_bf16 v[52:55], v[160:163], v[184:187], v[52:55]
	v_mfma_f32_16x16x32_bf16 v[48:51], v[176:179], v[184:187], v[48:51]
	v_mfma_f32_16x16x32_bf16 v[36:39], v[160:163], v[192:195], v[36:39]
	v_mfma_f32_16x16x32_bf16 v[32:35], v[176:179], v[192:195], v[32:35]
	v_mfma_f32_16x16x32_bf16 v[20:23], v[160:163], v[202:205], v[20:23]
	v_mfma_f32_16x16x32_bf16 v[16:19], v[176:179], v[202:205], v[16:19]
	v_mfma_f32_16x16x32_bf16 v[4:7], v[160:163], v[214:217], v[4:7]
	v_mfma_f32_16x16x32_bf16 v[0:3], v[176:179], v[214:217], v[0:3]
	v_mfma_f32_16x16x32_bf16 v[52:55], v[172:175], v[188:191], v[52:55]
	v_mfma_f32_16x16x32_bf16 v[48:51], v[180:183], v[188:191], v[48:51]
	v_mfma_f32_16x16x32_bf16 v[36:39], v[172:175], v[196:199], v[36:39]
	v_mfma_f32_16x16x32_bf16 v[32:35], v[180:183], v[196:199], v[32:35]
	v_mfma_f32_16x16x32_bf16 v[20:23], v[172:175], v[210:213], v[20:23]
	v_mfma_f32_16x16x32_bf16 v[16:19], v[180:183], v[210:213], v[16:19]
	v_mfma_f32_16x16x32_bf16 v[4:7], v[172:175], v[218:221], v[4:7]
	v_mfma_f32_16x16x32_bf16 v[0:3], v[180:183], v[218:221], v[0:3]
	s_barrier
	s_setprio 0
	s_add_i32 s38, 0, 0x18000
	s_add_i32 s39, 0, 0x1c000
	v_add_u32_e32 v156, s38, v169
	v_add_u32_e32 v180, s39, v169
	ds_read_b128 v[130:133], v156
	ds_read_b128 v[134:137], v156 offset:1024
	ds_read_b128 v[152:155], v156 offset:2048
	ds_read_b128 v[156:159], v156 offset:3072
	ds_read_b128 v[160:163], v180
	ds_read_b128 v[172:175], v180 offset:1024
	ds_read_b128 v[176:179], v180 offset:2048
	ds_read_b128 v[180:183], v180 offset:3072
	s_add_u32 s34, s86, 0x80000
	s_addc_u32 s35, s87, 0
	s_mov_b32 m0, s79
	ds_read_b128 v[184:187], v171 offset:32768
	ds_read_b128 v[188:191], v171 offset:33792
	ds_read_b128 v[192:195], v171 offset:34816
	ds_read_b128 v[196:199], v171 offset:35840
	ds_read_b128 v[202:205], v171 offset:36864
	ds_read_b128 v[210:213], v171 offset:37888
	ds_read_b128 v[214:217], v171 offset:38912
	ds_read_b128 v[218:221], v171 offset:39936
	global_load_lds_dwordx4 v146, s[34:35]
	s_mov_b32 m0, s90
	s_nop 0
	global_load_lds_dwordx4 v144, s[34:35]
	s_waitcnt vmcnt(8)
	s_waitcnt lgkmcnt(0)
	s_setprio 1
	s_barrier
	v_mfma_f32_16x16x32_bf16 v[126:129], v[130:133], v[184:187], v[126:129]
	v_mfma_f32_16x16x32_bf16 v[122:125], v[152:155], v[184:187], v[122:125]
	v_mfma_f32_16x16x32_bf16 v[110:113], v[130:133], v[192:195], v[110:113]
	v_mfma_f32_16x16x32_bf16 v[106:109], v[152:155], v[192:195], v[106:109]
	v_mfma_f32_16x16x32_bf16 v[92:95], v[130:133], v[202:205], v[92:95]
	v_mfma_f32_16x16x32_bf16 v[88:91], v[152:155], v[202:205], v[88:91]
	v_mfma_f32_16x16x32_bf16 v[76:79], v[130:133], v[214:217], v[76:79]
	v_mfma_f32_16x16x32_bf16 v[72:75], v[152:155], v[214:217], v[72:75]
	v_mfma_f32_16x16x32_bf16 v[126:129], v[134:137], v[188:191], v[126:129]
	v_mfma_f32_16x16x32_bf16 v[122:125], v[156:159], v[188:191], v[122:125]
	v_mfma_f32_16x16x32_bf16 v[110:113], v[134:137], v[196:199], v[110:113]
	v_mfma_f32_16x16x32_bf16 v[106:109], v[156:159], v[196:199], v[106:109]
	v_mfma_f32_16x16x32_bf16 v[92:95], v[134:137], v[210:213], v[92:95]
	v_mfma_f32_16x16x32_bf16 v[88:91], v[156:159], v[210:213], v[88:91]
	v_mfma_f32_16x16x32_bf16 v[76:79], v[134:137], v[218:221], v[76:79]
	v_mfma_f32_16x16x32_bf16 v[72:75], v[156:159], v[218:221], v[72:75]
	v_mfma_f32_16x16x32_bf16 v[118:121], v[160:163], v[184:187], v[118:121]
	v_mfma_f32_16x16x32_bf16 v[114:117], v[176:179], v[184:187], v[114:117]
	v_mfma_f32_16x16x32_bf16 v[102:105], v[160:163], v[192:195], v[102:105]
	v_mfma_f32_16x16x32_bf16 v[98:101], v[176:179], v[192:195], v[98:101]
	v_mfma_f32_16x16x32_bf16 v[84:87], v[160:163], v[202:205], v[84:87]
	v_mfma_f32_16x16x32_bf16 v[80:83], v[176:179], v[202:205], v[80:83]
	v_mfma_f32_16x16x32_bf16 v[68:71], v[160:163], v[214:217], v[68:71]
	v_mfma_f32_16x16x32_bf16 v[64:67], v[176:179], v[214:217], v[64:67]
	v_mfma_f32_16x16x32_bf16 v[118:121], v[172:175], v[188:191], v[118:121]
	v_mfma_f32_16x16x32_bf16 v[114:117], v[180:183], v[188:191], v[114:117]
	v_mfma_f32_16x16x32_bf16 v[102:105], v[172:175], v[196:199], v[102:105]
	v_mfma_f32_16x16x32_bf16 v[98:101], v[180:183], v[196:199], v[98:101]
	v_mfma_f32_16x16x32_bf16 v[84:87], v[172:175], v[210:213], v[84:87]
	v_mfma_f32_16x16x32_bf16 v[80:83], v[180:183], v[210:213], v[80:83]
	v_mfma_f32_16x16x32_bf16 v[68:71], v[172:175], v[218:221], v[68:71]
	v_mfma_f32_16x16x32_bf16 v[64:67], v[180:183], v[218:221], v[64:67]
	s_barrier
	s_setprio 0
	s_add_i32 s34, s38, s75
	v_lshl_add_u64 v[164:165], v[164:165], 0, s[64:65]
	s_mov_b32 m0, s34
	ds_read_b128 v[184:187], v171 offset:49152
	ds_read_b128 v[188:191], v171 offset:50176
	ds_read_b128 v[192:195], v171 offset:51200
	ds_read_b128 v[196:199], v171 offset:52224
	ds_read_b128 v[202:205], v171 offset:53248
	ds_read_b128 v[210:213], v171 offset:54272
	ds_read_b128 v[214:217], v171 offset:55296
	ds_read_b128 v[218:221], v171 offset:56320
	global_load_lds_dwordx4 v[164:165], off
	s_add_i32 m0, s34, 0x2000
	s_add_u32 s34, s84, 0x80080
	v_lshl_add_u64 v[164:165], v[222:223], 0, s[64:65]
	s_addc_u32 s35, s85, 0
	s_add_i32 s38, s39, s75
	global_load_lds_dwordx4 v[164:165], off
	s_mov_b32 m0, s38
	s_nop 0
	global_load_lds_dwordx4 v96, s[34:35]
	s_add_i32 m0, s38, 0x2000
	s_nop 0
	global_load_lds_dwordx4 v142, s[34:35]
	v_lshl_add_u64 v[164:165], v[224:225], 0, s[64:65]
	s_mov_b32 m0, s94
	s_nop 0
	global_load_lds_dwordx4 v[164:165], off
	v_lshl_add_u64 v[164:165], v[226:227], 0, s[64:65]
	s_mov_b32 m0, s95
	s_nop 0
	global_load_lds_dwordx4 v[164:165], off
	s_waitcnt vmcnt(8)
	s_waitcnt lgkmcnt(0)
	s_setprio 1
	s_barrier
	v_mfma_f32_16x16x32_bf16 v[60:63], v[130:133], v[184:187], v[60:63]
	v_mfma_f32_16x16x32_bf16 v[56:59], v[152:155], v[184:187], v[56:59]
	v_mfma_f32_16x16x32_bf16 v[44:47], v[130:133], v[192:195], v[44:47]
	v_mfma_f32_16x16x32_bf16 v[40:43], v[152:155], v[192:195], v[40:43]
	v_mfma_f32_16x16x32_bf16 v[28:31], v[130:133], v[202:205], v[28:31]
	v_mfma_f32_16x16x32_bf16 v[24:27], v[152:155], v[202:205], v[24:27]
	v_mfma_f32_16x16x32_bf16 v[12:15], v[130:133], v[214:217], v[12:15]
	v_mfma_f32_16x16x32_bf16 v[8:11], v[152:155], v[214:217], v[8:11]
	v_mfma_f32_16x16x32_bf16 v[60:63], v[134:137], v[188:191], v[60:63]
	v_mfma_f32_16x16x32_bf16 v[56:59], v[156:159], v[188:191], v[56:59]
	v_mfma_f32_16x16x32_bf16 v[44:47], v[134:137], v[196:199], v[44:47]
	v_mfma_f32_16x16x32_bf16 v[40:43], v[156:159], v[196:199], v[40:43]
	v_mfma_f32_16x16x32_bf16 v[28:31], v[134:137], v[210:213], v[28:31]
	v_mfma_f32_16x16x32_bf16 v[24:27], v[156:159], v[210:213], v[24:27]
	v_mfma_f32_16x16x32_bf16 v[12:15], v[134:137], v[218:221], v[12:15]
	v_mfma_f32_16x16x32_bf16 v[8:11], v[156:159], v[218:221], v[8:11]
	v_mfma_f32_16x16x32_bf16 v[52:55], v[160:163], v[184:187], v[52:55]
	v_mfma_f32_16x16x32_bf16 v[48:51], v[176:179], v[184:187], v[48:51]
	v_mfma_f32_16x16x32_bf16 v[36:39], v[160:163], v[192:195], v[36:39]
	v_mfma_f32_16x16x32_bf16 v[32:35], v[176:179], v[192:195], v[32:35]
	v_mfma_f32_16x16x32_bf16 v[20:23], v[160:163], v[202:205], v[20:23]
	v_mfma_f32_16x16x32_bf16 v[16:19], v[176:179], v[202:205], v[16:19]
	v_mfma_f32_16x16x32_bf16 v[4:7], v[160:163], v[214:217], v[4:7]
	v_mfma_f32_16x16x32_bf16 v[0:3], v[176:179], v[214:217], v[0:3]
	v_mfma_f32_16x16x32_bf16 v[52:55], v[172:175], v[188:191], v[52:55]
	v_mfma_f32_16x16x32_bf16 v[48:51], v[180:183], v[188:191], v[48:51]
	v_mfma_f32_16x16x32_bf16 v[36:39], v[172:175], v[196:199], v[36:39]
	v_mfma_f32_16x16x32_bf16 v[32:35], v[180:183], v[196:199], v[32:35]
	v_mfma_f32_16x16x32_bf16 v[20:23], v[172:175], v[210:213], v[20:23]
	v_mfma_f32_16x16x32_bf16 v[16:19], v[180:183], v[210:213], v[16:19]
	v_mfma_f32_16x16x32_bf16 v[4:7], v[172:175], v[218:221], v[4:7]
	v_mfma_f32_16x16x32_bf16 v[0:3], v[180:183], v[218:221], v[0:3]
	s_barrier
	s_setprio 0
	s_add_i32 s33, s33, 2
	s_add_u32 s44, s44, 0x100
	s_addc_u32 s45, s45, 0
	s_add_u32 s28, s28, 0x100
	s_addc_u32 s31, s31, 0
	s_cmp_gt_u32 s33, 29
	s_cbranch_scc0 .LBB0_1038
	v_mov_b32_e32 v243, 1
	v_readlane_b32 s0, v251, 54
	v_readlane_b32 s1, v251, 55
	s_and_b64 vcc, exec, s[0:1]
	s_cbranch_vccz .LBB0_1041
	s_barrier

.LBB0_1265:
	s_add_u32 s35, s42, 0xffe00080
	s_addc_u32 s44, s43, -1
	s_add_i32 s54, 0, 0x10000
	s_cmpk_eq_i32 s33, 0x7c
	s_cselect_b32 s53, s12, s44
	s_cselect_b32 s52, s17, s35
	v_add_u32_e32 v148, s54, v153
	s_cselect_b32 s45, s5, s28
	s_cselect_b32 s44, s18, s20
	s_add_i32 s35, 0, 0x14000
	ds_read_b128 v[144:147], v148
	ds_read_b128 v[154:157], v148 offset:1024
	ds_read_b128 v[160:163], v148 offset:2048
	ds_read_b128 v[164:167], v148 offset:3072
	v_add_u32_e32 v148, s35, v153
	ds_read_b128 v[168:171], v148
	ds_read_b128 v[172:175], v148 offset:1024
	ds_read_b128 v[176:179], v148 offset:2048
	ds_read_b128 v[180:183], v148 offset:3072
	s_add_i32 m0, s59, 0xc000
	ds_read_b128 v[184:187], v159
	ds_read_b128 v[188:191], v159 offset:1024
	ds_read_b128 v[192:195], v159 offset:2048
	ds_read_b128 v[196:199], v159 offset:3072
	ds_read_b128 v[202:205], v159 offset:4096
	ds_read_b128 v[210:213], v159 offset:5120
	ds_read_b128 v[214:217], v159 offset:6144
	ds_read_b128 v[218:221], v159 offset:7168
	global_load_lds_dwordx4 v140, s[42:43]
	s_add_i32 m0, s59, 0xe000
	s_nop 0
	global_load_lds_dwordx4 v142, s[42:43]
	v_cmp_ne_u32_e32 vcc, 0, v243
	s_cbranch_vccnz .Lrx_G_DN_0
	s_waitcnt vmcnt(8)
.Lrx_G_DN_0:
	s_waitcnt vmcnt(44)
	s_waitcnt lgkmcnt(0)
	s_setprio 1
	s_barrier
	v_mfma_f32_16x16x32_bf16 v[126:129], v[144:147], v[184:187], v[126:129]
	v_mfma_f32_16x16x32_bf16 v[122:125], v[160:163], v[184:187], v[122:125]
	v_mfma_f32_16x16x32_bf16 v[110:113], v[144:147], v[192:195], v[110:113]
	v_mfma_f32_16x16x32_bf16 v[106:109], v[160:163], v[192:195], v[106:109]
	v_mfma_f32_16x16x32_bf16 v[92:95], v[144:147], v[202:205], v[92:95]
	v_mfma_f32_16x16x32_bf16 v[88:91], v[160:163], v[202:205], v[88:91]
	v_mfma_f32_16x16x32_bf16 v[76:79], v[144:147], v[214:217], v[76:79]
	v_mfma_f32_16x16x32_bf16 v[72:75], v[160:163], v[214:217], v[72:75]
	v_mfma_f32_16x16x32_bf16 v[126:129], v[154:157], v[188:191], v[126:129]
	v_mfma_f32_16x16x32_bf16 v[122:125], v[164:167], v[188:191], v[122:125]
	v_mfma_f32_16x16x32_bf16 v[110:113], v[154:157], v[196:199], v[110:113]
	v_mfma_f32_16x16x32_bf16 v[106:109], v[164:167], v[196:199], v[106:109]
	v_mfma_f32_16x16x32_bf16 v[92:95], v[154:157], v[210:213], v[92:95]
	v_mfma_f32_16x16x32_bf16 v[88:91], v[164:167], v[210:213], v[88:91]
	v_mfma_f32_16x16x32_bf16 v[76:79], v[154:157], v[218:221], v[76:79]
	v_mfma_f32_16x16x32_bf16 v[72:75], v[164:167], v[218:221], v[72:75]
	v_mfma_f32_16x16x32_bf16 v[118:121], v[168:171], v[184:187], v[118:121]
	v_mfma_f32_16x16x32_bf16 v[114:117], v[176:179], v[184:187], v[114:117]
	v_mfma_f32_16x16x32_bf16 v[102:105], v[168:171], v[192:195], v[102:105]
	v_mfma_f32_16x16x32_bf16 v[98:101], v[176:179], v[192:195], v[98:101]
	v_mfma_f32_16x16x32_bf16 v[84:87], v[168:171], v[202:205], v[84:87]
	v_mfma_f32_16x16x32_bf16 v[80:83], v[176:179], v[202:205], v[80:83]
	v_mfma_f32_16x16x32_bf16 v[68:71], v[168:171], v[214:217], v[68:71]
	v_mfma_f32_16x16x32_bf16 v[64:67], v[176:179], v[214:217], v[64:67]
	v_mfma_f32_16x16x32_bf16 v[118:121], v[172:175], v[188:191], v[118:121]
	v_mfma_f32_16x16x32_bf16 v[114:117], v[180:183], v[188:191], v[114:117]
	v_mfma_f32_16x16x32_bf16 v[102:105], v[172:175], v[196:199], v[102:105]
	v_mfma_f32_16x16x32_bf16 v[98:101], v[180:183], v[196:199], v[98:101]
	v_mfma_f32_16x16x32_bf16 v[84:87], v[172:175], v[210:213], v[84:87]
	v_mfma_f32_16x16x32_bf16 v[80:83], v[180:183], v[210:213], v[80:83]
	v_mfma_f32_16x16x32_bf16 v[68:71], v[172:175], v[218:221], v[68:71]
	v_mfma_f32_16x16x32_bf16 v[64:67], v[180:183], v[218:221], v[64:67]
	s_barrier
	s_setprio 0
	s_add_i32 s54, s54, s75
	v_lshl_add_u64 v[148:149], s[44:45], 0, v[96:97]
	s_mov_b32 m0, s54
	ds_read_b128 v[184:187], v159 offset:16384
	ds_read_b128 v[188:191], v159 offset:17408
	ds_read_b128 v[192:195], v159 offset:18432
	ds_read_b128 v[196:199], v159 offset:19456
	ds_read_b128 v[202:205], v159 offset:20480
	ds_read_b128 v[210:213], v159 offset:21504
	ds_read_b128 v[214:217], v159 offset:22528
	ds_read_b128 v[218:221], v159 offset:23552
	global_load_lds_dwordx4 v96, s[44:45]
	s_add_i32 m0, s54, 0x2000
	s_add_u32 s54, s44, 0x200000
	v_lshl_add_u64 v[222:223], s[44:45], 0, v[134:135]
	s_addc_u32 s55, s45, 0
	s_add_i32 s35, s35, s75
	global_load_lds_dwordx4 v134, s[44:45]
	s_mov_b32 m0, s35
	v_lshl_add_u64 v[226:227], s[52:53], 0, v[136:137]
	global_load_lds_dwordx4 v96, s[54:55]
	s_add_i32 m0, s35, 0x2000
	s_nop 0
	global_load_lds_dwordx4 v134, s[54:55]
	v_lshl_add_u64 v[224:225], s[52:53], 0, v[138:139]
	s_mov_b32 m0, s59
	s_nop 0
	global_load_lds_dwordx4 v138, s[52:53]
	s_mov_b32 m0, s68
	s_nop 0
	global_load_lds_dwordx4 v136, s[52:53]
	v_cmp_ne_u32_e32 vcc, 0, v243
	s_cbranch_vccnz .Lrx_G_DN_1
	s_waitcnt vmcnt(8)
.Lrx_G_DN_1:
	s_waitcnt vmcnt(44)
	v_mov_b32_e32 v243, 0
	s_waitcnt lgkmcnt(0)
	s_setprio 1
	s_barrier
	v_mfma_f32_16x16x32_bf16 v[60:63], v[144:147], v[184:187], v[60:63]
	v_mfma_f32_16x16x32_bf16 v[56:59], v[160:163], v[184:187], v[56:59]
	v_mfma_f32_16x16x32_bf16 v[44:47], v[144:147], v[192:195], v[44:47]
	v_mfma_f32_16x16x32_bf16 v[40:43], v[160:163], v[192:195], v[40:43]
	v_mfma_f32_16x16x32_bf16 v[28:31], v[144:147], v[202:205], v[28:31]
	v_mfma_f32_16x16x32_bf16 v[24:27], v[160:163], v[202:205], v[24:27]
	v_mfma_f32_16x16x32_bf16 v[12:15], v[144:147], v[214:217], v[12:15]
	v_mfma_f32_16x16x32_bf16 v[8:11], v[160:163], v[214:217], v[8:11]
	v_mfma_f32_16x16x32_bf16 v[60:63], v[154:157], v[188:191], v[60:63]
	v_mfma_f32_16x16x32_bf16 v[56:59], v[164:167], v[188:191], v[56:59]
	v_mfma_f32_16x16x32_bf16 v[44:47], v[154:157], v[196:199], v[44:47]
	v_mfma_f32_16x16x32_bf16 v[40:43], v[164:167], v[196:199], v[40:43]
	v_mfma_f32_16x16x32_bf16 v[28:31], v[154:157], v[210:213], v[28:31]
	v_mfma_f32_16x16x32_bf16 v[24:27], v[164:167], v[210:213], v[24:27]
	v_mfma_f32_16x16x32_bf16 v[12:15], v[154:157], v[218:221], v[12:15]
	v_mfma_f32_16x16x32_bf16 v[8:11], v[164:167], v[218:221], v[8:11]
	v_mfma_f32_16x16x32_bf16 v[52:55], v[168:171], v[184:187], v[52:55]
	v_mfma_f32_16x16x32_bf16 v[48:51], v[176:179], v[184:187], v[48:51]
	v_mfma_f32_16x16x32_bf16 v[36:39], v[168:171], v[192:195], v[36:39]
	v_mfma_f32_16x16x32_bf16 v[32:35], v[176:179], v[192:195], v[32:35]
	v_mfma_f32_16x16x32_bf16 v[20:23], v[168:171], v[202:205], v[20:23]
	v_mfma_f32_16x16x32_bf16 v[16:19], v[176:179], v[202:205], v[16:19]
	v_mfma_f32_16x16x32_bf16 v[4:7], v[168:171], v[214:217], v[4:7]
	v_mfma_f32_16x16x32_bf16 v[0:3], v[176:179], v[214:217], v[0:3]
	v_mfma_f32_16x16x32_bf16 v[52:55], v[172:175], v[188:191], v[52:55]
	v_mfma_f32_16x16x32_bf16 v[48:51], v[180:183], v[188:191], v[48:51]
	v_mfma_f32_16x16x32_bf16 v[36:39], v[172:175], v[196:199], v[36:39]
	v_mfma_f32_16x16x32_bf16 v[32:35], v[180:183], v[196:199], v[32:35]
	v_mfma_f32_16x16x32_bf16 v[20:23], v[172:175], v[210:213], v[20:23]
	v_mfma_f32_16x16x32_bf16 v[16:19], v[180:183], v[210:213], v[16:19]
	v_mfma_f32_16x16x32_bf16 v[4:7], v[172:175], v[218:221], v[4:7]
	v_mfma_f32_16x16x32_bf16 v[0:3], v[180:183], v[218:221], v[0:3]
	s_barrier
	s_setprio 0
	s_add_i32 s35, 0, 0x18000
	s_add_i32 s54, 0, 0x1c000
	v_add_u32_e32 v164, s35, v153
	v_add_u32_e32 v180, s54, v153
	ds_read_b128 v[144:147], v164
	ds_read_b128 v[154:157], v164 offset:1024
	ds_read_b128 v[160:163], v164 offset:2048
	ds_read_b128 v[164:167], v164 offset:3072
	ds_read_b128 v[168:171], v180
	ds_read_b128 v[172:175], v180 offset:1024
	ds_read_b128 v[176:179], v180 offset:2048
	ds_read_b128 v[180:183], v180 offset:3072
	s_add_u32 s52, s52, 0x200000
	s_addc_u32 s53, s53, 0
	s_mov_b32 m0, s69
	ds_read_b128 v[184:187], v159 offset:32768
	ds_read_b128 v[188:191], v159 offset:33792
	ds_read_b128 v[192:195], v159 offset:34816
	ds_read_b128 v[196:199], v159 offset:35840
	ds_read_b128 v[202:205], v159 offset:36864
	ds_read_b128 v[210:213], v159 offset:37888
	ds_read_b128 v[214:217], v159 offset:38912
	ds_read_b128 v[218:221], v159 offset:39936
	global_load_lds_dwordx4 v138, s[52:53]
	s_mov_b32 m0, s79
	s_nop 0
	global_load_lds_dwordx4 v136, s[52:53]
	s_waitcnt vmcnt(8)
	s_waitcnt lgkmcnt(0)
	s_setprio 1
	s_barrier
	v_mfma_f32_16x16x32_bf16 v[126:129], v[144:147], v[184:187], v[126:129]
	v_mfma_f32_16x16x32_bf16 v[122:125], v[160:163], v[184:187], v[122:125]
	v_mfma_f32_16x16x32_bf16 v[110:113], v[144:147], v[192:195], v[110:113]
	v_mfma_f32_16x16x32_bf16 v[106:109], v[160:163], v[192:195], v[106:109]
	v_mfma_f32_16x16x32_bf16 v[92:95], v[144:147], v[202:205], v[92:95]
	v_mfma_f32_16x16x32_bf16 v[88:91], v[160:163], v[202:205], v[88:91]
	v_mfma_f32_16x16x32_bf16 v[76:79], v[144:147], v[214:217], v[76:79]
	v_mfma_f32_16x16x32_bf16 v[72:75], v[160:163], v[214:217], v[72:75]
	v_mfma_f32_16x16x32_bf16 v[126:129], v[154:157], v[188:191], v[126:129]
	v_mfma_f32_16x16x32_bf16 v[122:125], v[164:167], v[188:191], v[122:125]
	v_mfma_f32_16x16x32_bf16 v[110:113], v[154:157], v[196:199], v[110:113]
	v_mfma_f32_16x16x32_bf16 v[106:109], v[164:167], v[196:199], v[106:109]
	v_mfma_f32_16x16x32_bf16 v[92:95], v[154:157], v[210:213], v[92:95]
	v_mfma_f32_16x16x32_bf16 v[88:91], v[164:167], v[210:213], v[88:91]
	v_mfma_f32_16x16x32_bf16 v[76:79], v[154:157], v[218:221], v[76:79]
	v_mfma_f32_16x16x32_bf16 v[72:75], v[164:167], v[218:221], v[72:75]
	v_mfma_f32_16x16x32_bf16 v[118:121], v[168:171], v[184:187], v[118:121]
	v_mfma_f32_16x16x32_bf16 v[114:117], v[176:179], v[184:187], v[114:117]
	v_mfma_f32_16x16x32_bf16 v[102:105], v[168:171], v[192:195], v[102:105]
	v_mfma_f32_16x16x32_bf16 v[98:101], v[176:179], v[192:195], v[98:101]
	v_mfma_f32_16x16x32_bf16 v[84:87], v[168:171], v[202:205], v[84:87]
	v_mfma_f32_16x16x32_bf16 v[80:83], v[176:179], v[202:205], v[80:83]
	v_mfma_f32_16x16x32_bf16 v[68:71], v[168:171], v[214:217], v[68:71]
	v_mfma_f32_16x16x32_bf16 v[64:67], v[176:179], v[214:217], v[64:67]
	v_mfma_f32_16x16x32_bf16 v[118:121], v[172:175], v[188:191], v[118:121]
	v_mfma_f32_16x16x32_bf16 v[114:117], v[180:183], v[188:191], v[114:117]
	v_mfma_f32_16x16x32_bf16 v[102:105], v[172:175], v[196:199], v[102:105]
	v_mfma_f32_16x16x32_bf16 v[98:101], v[180:183], v[196:199], v[98:101]
	v_mfma_f32_16x16x32_bf16 v[84:87], v[172:175], v[210:213], v[84:87]
	v_mfma_f32_16x16x32_bf16 v[80:83], v[180:183], v[210:213], v[80:83]
	v_mfma_f32_16x16x32_bf16 v[68:71], v[172:175], v[218:221], v[68:71]
	v_mfma_f32_16x16x32_bf16 v[64:67], v[180:183], v[218:221], v[64:67]
	s_barrier
	s_setprio 0
	s_add_i32 s35, s35, s75
	v_lshl_add_u64 v[148:149], v[148:149], 0, s[64:65]
	s_mov_b32 m0, s35
	ds_read_b128 v[184:187], v159 offset:49152
	ds_read_b128 v[188:191], v159 offset:50176
	ds_read_b128 v[192:195], v159 offset:51200
	ds_read_b128 v[196:199], v159 offset:52224
	ds_read_b128 v[202:205], v159 offset:53248
	ds_read_b128 v[210:213], v159 offset:54272
	ds_read_b128 v[214:217], v159 offset:55296
	ds_read_b128 v[218:221], v159 offset:56320
	global_load_lds_dwordx4 v[148:149], off
	s_add_i32 m0, s35, 0x2000
	s_add_u32 s44, s44, 0x200080
	v_lshl_add_u64 v[148:149], v[222:223], 0, s[64:65]
	s_addc_u32 s45, s45, 0
	s_add_i32 s35, s54, s75
	global_load_lds_dwordx4 v[148:149], off
	s_mov_b32 m0, s35
	s_nop 0
	global_load_lds_dwordx4 v96, s[44:45]
	s_add_i32 m0, s35, 0x2000
	s_nop 0
	global_load_lds_dwordx4 v134, s[44:45]
	v_lshl_add_u64 v[148:149], v[224:225], 0, s[64:65]
	s_mov_b32 m0, s10
	s_nop 0
	global_load_lds_dwordx4 v[148:149], off
	v_lshl_add_u64 v[148:149], v[226:227], 0, s[64:65]
	s_mov_b32 m0, s77
	s_nop 0
	global_load_lds_dwordx4 v[148:149], off
	s_waitcnt vmcnt(8)
	s_waitcnt lgkmcnt(0)
	s_setprio 1
	s_barrier
	v_mfma_f32_16x16x32_bf16 v[60:63], v[144:147], v[184:187], v[60:63]
	v_mfma_f32_16x16x32_bf16 v[56:59], v[160:163], v[184:187], v[56:59]
	v_mfma_f32_16x16x32_bf16 v[44:47], v[144:147], v[192:195], v[44:47]
	v_mfma_f32_16x16x32_bf16 v[40:43], v[160:163], v[192:195], v[40:43]
	v_mfma_f32_16x16x32_bf16 v[28:31], v[144:147], v[202:205], v[28:31]
	v_mfma_f32_16x16x32_bf16 v[24:27], v[160:163], v[202:205], v[24:27]
	v_mfma_f32_16x16x32_bf16 v[12:15], v[144:147], v[214:217], v[12:15]
	v_mfma_f32_16x16x32_bf16 v[8:11], v[160:163], v[214:217], v[8:11]
	v_mfma_f32_16x16x32_bf16 v[60:63], v[154:157], v[188:191], v[60:63]
	v_mfma_f32_16x16x32_bf16 v[56:59], v[164:167], v[188:191], v[56:59]
	v_mfma_f32_16x16x32_bf16 v[44:47], v[154:157], v[196:199], v[44:47]
	v_mfma_f32_16x16x32_bf16 v[40:43], v[164:167], v[196:199], v[40:43]
	v_mfma_f32_16x16x32_bf16 v[28:31], v[154:157], v[210:213], v[28:31]
	v_mfma_f32_16x16x32_bf16 v[24:27], v[164:167], v[210:213], v[24:27]
	v_mfma_f32_16x16x32_bf16 v[12:15], v[154:157], v[218:221], v[12:15]
	v_mfma_f32_16x16x32_bf16 v[8:11], v[164:167], v[218:221], v[8:11]
	v_mfma_f32_16x16x32_bf16 v[52:55], v[168:171], v[184:187], v[52:55]
	v_mfma_f32_16x16x32_bf16 v[48:51], v[176:179], v[184:187], v[48:51]
	v_mfma_f32_16x16x32_bf16 v[36:39], v[168:171], v[192:195], v[36:39]
	v_mfma_f32_16x16x32_bf16 v[32:35], v[176:179], v[192:195], v[32:35]
	v_mfma_f32_16x16x32_bf16 v[20:23], v[168:171], v[202:205], v[20:23]
	v_mfma_f32_16x16x32_bf16 v[16:19], v[176:179], v[202:205], v[16:19]
	v_mfma_f32_16x16x32_bf16 v[4:7], v[168:171], v[214:217], v[4:7]
	v_mfma_f32_16x16x32_bf16 v[0:3], v[176:179], v[214:217], v[0:3]
	v_mfma_f32_16x16x32_bf16 v[52:55], v[172:175], v[188:191], v[52:55]
	v_mfma_f32_16x16x32_bf16 v[48:51], v[180:183], v[188:191], v[48:51]
	v_mfma_f32_16x16x32_bf16 v[36:39], v[172:175], v[196:199], v[36:39]
	v_mfma_f32_16x16x32_bf16 v[32:35], v[180:183], v[196:199], v[32:35]
	v_mfma_f32_16x16x32_bf16 v[20:23], v[172:175], v[210:213], v[20:23]
	v_mfma_f32_16x16x32_bf16 v[16:19], v[180:183], v[210:213], v[16:19]
	v_mfma_f32_16x16x32_bf16 v[4:7], v[172:175], v[218:221], v[4:7]
	v_mfma_f32_16x16x32_bf16 v[0:3], v[180:183], v[218:221], v[0:3]
	s_barrier
	s_setprio 0
	s_add_i32 s33, s33, 2
	s_add_u32 s42, s42, 0x100
	s_addc_u32 s43, s43, 0
	s_add_u32 s20, s20, 0x100
	s_addc_u32 s28, s28, 0
	s_cmpk_gt_u32 s33, 0x7d
	s_cbranch_scc0 .LBB0_1265
	v_mov_b32_e32 v243, 1
	v_readlane_b32 s6, v251, 54
	v_readlane_b32 s7, v251, 55
	s_and_b64 vcc, exec, s[6:7]
	s_movk_i32 s53, 0x6000
	s_cbranch_vccz .LBB0_1268
	s_barrier

.LBB0_1284:
	s_add_u32 s33, s52, 0xfff80080
	s_addc_u32 s38, s53, -1
	s_add_i32 s39, 0, 0x10000
	s_cmp_eq_u32 s28, 28
	s_cselect_b32 s83, s3, s38
	s_cselect_b32 s82, s12, s33
	v_add_u32_e32 v144, s39, v150
	s_cselect_b32 s69, s17, s25
	s_cselect_b32 s68, s18, s20
	s_add_i32 s33, 0, 0x14000
	ds_read_b128 v[154:157], v144
	ds_read_b128 v[158:161], v144 offset:1024
	ds_read_b128 v[162:165], v144 offset:2048
	ds_read_b128 v[166:169], v144 offset:3072
	v_add_u32_e32 v144, s33, v150
	ds_read_b128 v[170:173], v144
	ds_read_b128 v[174:177], v144 offset:1024
	ds_read_b128 v[178:181], v144 offset:2048
	ds_read_b128 v[182:185], v144 offset:3072
	s_add_i32 m0, s34, 0xc000
	ds_read_b128 v[186:189], v152
	ds_read_b128 v[190:193], v152 offset:1024
	ds_read_b128 v[194:197], v152 offset:2048
	ds_read_b128 v[202:205], v152 offset:3072
	ds_read_b128 v[210:213], v152 offset:4096
	ds_read_b128 v[214:217], v152 offset:5120
	ds_read_b128 v[218:221], v152 offset:6144
	ds_read_b128 v[222:225], v152 offset:7168
	global_load_lds_dwordx4 v140, s[52:53]
	s_add_i32 m0, s34, 0xe000
	s_nop 0
	global_load_lds_dwordx4 v142, s[52:53]
	v_cmp_ne_u32_e32 vcc, 0, v243
	s_cbranch_vccnz .Lrx_G_UP_0
	s_waitcnt vmcnt(8)
.Lrx_G_UP_0:
	s_waitcnt vmcnt(24)
	s_waitcnt lgkmcnt(0)
	s_setprio 1
	s_barrier
	v_mfma_f32_16x16x32_bf16 v[126:129], v[154:157], v[186:189], v[126:129]
	v_mfma_f32_16x16x32_bf16 v[122:125], v[162:165], v[186:189], v[122:125]
	v_mfma_f32_16x16x32_bf16 v[110:113], v[154:157], v[194:197], v[110:113]
	v_mfma_f32_16x16x32_bf16 v[106:109], v[162:165], v[194:197], v[106:109]
	v_mfma_f32_16x16x32_bf16 v[92:95], v[154:157], v[210:213], v[92:95]
	v_mfma_f32_16x16x32_bf16 v[88:91], v[162:165], v[210:213], v[88:91]
	v_mfma_f32_16x16x32_bf16 v[76:79], v[154:157], v[218:221], v[76:79]
	v_mfma_f32_16x16x32_bf16 v[72:75], v[162:165], v[218:221], v[72:75]
	v_mfma_f32_16x16x32_bf16 v[126:129], v[158:161], v[190:193], v[126:129]
	v_mfma_f32_16x16x32_bf16 v[122:125], v[166:169], v[190:193], v[122:125]
	v_mfma_f32_16x16x32_bf16 v[110:113], v[158:161], v[202:205], v[110:113]
	v_mfma_f32_16x16x32_bf16 v[106:109], v[166:169], v[202:205], v[106:109]
	v_mfma_f32_16x16x32_bf16 v[92:95], v[158:161], v[214:217], v[92:95]
	v_mfma_f32_16x16x32_bf16 v[88:91], v[166:169], v[214:217], v[88:91]
	v_mfma_f32_16x16x32_bf16 v[76:79], v[158:161], v[222:225], v[76:79]
	v_mfma_f32_16x16x32_bf16 v[72:75], v[166:169], v[222:225], v[72:75]
	v_mfma_f32_16x16x32_bf16 v[118:121], v[170:173], v[186:189], v[118:121]
	v_mfma_f32_16x16x32_bf16 v[114:117], v[178:181], v[186:189], v[114:117]
	v_mfma_f32_16x16x32_bf16 v[102:105], v[170:173], v[194:197], v[102:105]
	v_mfma_f32_16x16x32_bf16 v[98:101], v[178:181], v[194:197], v[98:101]
	v_mfma_f32_16x16x32_bf16 v[84:87], v[170:173], v[210:213], v[84:87]
	v_mfma_f32_16x16x32_bf16 v[80:83], v[178:181], v[210:213], v[80:83]
	v_mfma_f32_16x16x32_bf16 v[68:71], v[170:173], v[218:221], v[68:71]
	v_mfma_f32_16x16x32_bf16 v[64:67], v[178:181], v[218:221], v[64:67]
	v_mfma_f32_16x16x32_bf16 v[118:121], v[174:177], v[190:193], v[118:121]
	v_mfma_f32_16x16x32_bf16 v[114:117], v[182:185], v[190:193], v[114:117]
	v_mfma_f32_16x16x32_bf16 v[102:105], v[174:177], v[202:205], v[102:105]
	v_mfma_f32_16x16x32_bf16 v[98:101], v[182:185], v[202:205], v[98:101]
	v_mfma_f32_16x16x32_bf16 v[84:87], v[174:177], v[214:217], v[84:87]
	v_mfma_f32_16x16x32_bf16 v[80:83], v[182:185], v[214:217], v[80:83]
	v_mfma_f32_16x16x32_bf16 v[68:71], v[174:177], v[222:225], v[68:71]
	v_mfma_f32_16x16x32_bf16 v[64:67], v[182:185], v[222:225], v[64:67]
	s_barrier
	s_setprio 0
	s_add_i32 s38, s39, s75
	v_lshl_add_u64 v[144:145], s[68:69], 0, v[96:97]
	s_mov_b32 m0, s38
	ds_read_b128 v[186:189], v152 offset:16384
	ds_read_b128 v[190:193], v152 offset:17408
	ds_read_b128 v[194:197], v152 offset:18432
	ds_read_b128 v[202:205], v152 offset:19456
	ds_read_b128 v[210:213], v152 offset:20480
	ds_read_b128 v[214:217], v152 offset:21504
	ds_read_b128 v[218:221], v152 offset:22528
	ds_read_b128 v[222:225], v152 offset:23552
	global_load_lds_dwordx4 v96, s[68:69]
	s_add_i32 m0, s38, 0x2000
	s_add_u32 s38, s68, 0x80000
	v_lshl_add_u64 v[198:199], s[68:69], 0, v[134:135]
	s_addc_u32 s39, s69, 0
	s_add_i32 s33, s33, s75
	global_load_lds_dwordx4 v134, s[68:69]
	s_mov_b32 m0, s33
	v_lshl_add_u64 v[228:229], s[82:83], 0, v[136:137]
	global_load_lds_dwordx4 v96, s[38:39]
	s_add_i32 m0, s33, 0x2000
	s_nop 0
	global_load_lds_dwordx4 v134, s[38:39]
	v_lshl_add_u64 v[226:227], s[82:83], 0, v[138:139]
	s_mov_b32 m0, s34
	s_nop 0
	global_load_lds_dwordx4 v138, s[82:83]
	s_mov_b32 m0, s35
	s_nop 0
	global_load_lds_dwordx4 v136, s[82:83]
	v_cmp_ne_u32_e32 vcc, 0, v243
	s_cbranch_vccnz .Lrx_G_UP_1
	s_waitcnt vmcnt(8)
.Lrx_G_UP_1:
	s_waitcnt vmcnt(24)
	v_mov_b32_e32 v243, 0
	s_waitcnt lgkmcnt(0)
	s_setprio 1
	s_barrier
	v_mfma_f32_16x16x32_bf16 v[60:63], v[154:157], v[186:189], v[60:63]
	v_mfma_f32_16x16x32_bf16 v[56:59], v[162:165], v[186:189], v[56:59]
	v_mfma_f32_16x16x32_bf16 v[44:47], v[154:157], v[194:197], v[44:47]
	v_mfma_f32_16x16x32_bf16 v[40:43], v[162:165], v[194:197], v[40:43]
	v_mfma_f32_16x16x32_bf16 v[28:31], v[154:157], v[210:213], v[28:31]
	v_mfma_f32_16x16x32_bf16 v[24:27], v[162:165], v[210:213], v[24:27]
	v_mfma_f32_16x16x32_bf16 v[12:15], v[154:157], v[218:221], v[12:15]
	v_mfma_f32_16x16x32_bf16 v[8:11], v[162:165], v[218:221], v[8:11]
	v_mfma_f32_16x16x32_bf16 v[60:63], v[158:161], v[190:193], v[60:63]
	v_mfma_f32_16x16x32_bf16 v[56:59], v[166:169], v[190:193], v[56:59]
	v_mfma_f32_16x16x32_bf16 v[44:47], v[158:161], v[202:205], v[44:47]
	v_mfma_f32_16x16x32_bf16 v[40:43], v[166:169], v[202:205], v[40:43]
	v_mfma_f32_16x16x32_bf16 v[28:31], v[158:161], v[214:217], v[28:31]
	v_mfma_f32_16x16x32_bf16 v[24:27], v[166:169], v[214:217], v[24:27]
	v_mfma_f32_16x16x32_bf16 v[12:15], v[158:161], v[222:225], v[12:15]
	v_mfma_f32_16x16x32_bf16 v[8:11], v[166:169], v[222:225], v[8:11]
	v_mfma_f32_16x16x32_bf16 v[52:55], v[170:173], v[186:189], v[52:55]
	v_mfma_f32_16x16x32_bf16 v[48:51], v[178:181], v[186:189], v[48:51]
	v_mfma_f32_16x16x32_bf16 v[36:39], v[170:173], v[194:197], v[36:39]
	v_mfma_f32_16x16x32_bf16 v[32:35], v[178:181], v[194:197], v[32:35]
	v_mfma_f32_16x16x32_bf16 v[20:23], v[170:173], v[210:213], v[20:23]
	v_mfma_f32_16x16x32_bf16 v[16:19], v[178:181], v[210:213], v[16:19]
	v_mfma_f32_16x16x32_bf16 v[4:7], v[170:173], v[218:221], v[4:7]
	v_mfma_f32_16x16x32_bf16 v[0:3], v[178:181], v[218:221], v[0:3]
	v_mfma_f32_16x16x32_bf16 v[52:55], v[174:177], v[190:193], v[52:55]
	v_mfma_f32_16x16x32_bf16 v[48:51], v[182:185], v[190:193], v[48:51]
	v_mfma_f32_16x16x32_bf16 v[36:39], v[174:177], v[202:205], v[36:39]
	v_mfma_f32_16x16x32_bf16 v[32:35], v[182:185], v[202:205], v[32:35]
	v_mfma_f32_16x16x32_bf16 v[20:23], v[174:177], v[214:217], v[20:23]
	v_mfma_f32_16x16x32_bf16 v[16:19], v[182:185], v[214:217], v[16:19]
	v_mfma_f32_16x16x32_bf16 v[4:7], v[174:177], v[222:225], v[4:7]
	v_mfma_f32_16x16x32_bf16 v[0:3], v[182:185], v[222:225], v[0:3]
	s_barrier
	s_setprio 0
	s_add_i32 s33, 0, 0x18000
	v_add_u32_e32 v153, s33, v150
	s_add_i32 s54, 0, 0x1c000
	ds_read_b128 v[154:157], v153
	ds_read_b128 v[158:161], v153 offset:1024
	ds_read_b128 v[162:165], v153 offset:2048
	ds_read_b128 v[166:169], v153 offset:3072
	v_add_u32_e32 v153, s54, v150
	ds_read_b128 v[170:173], v153
	ds_read_b128 v[174:177], v153 offset:1024
	ds_read_b128 v[178:181], v153 offset:2048
	ds_read_b128 v[182:185], v153 offset:3072
	s_add_u32 s38, s82, 0x80000
	s_addc_u32 s39, s83, 0
	s_mov_b32 m0, s50
	ds_read_b128 v[186:189], v152 offset:32768
	ds_read_b128 v[190:193], v152 offset:33792
	ds_read_b128 v[194:197], v152 offset:34816
	ds_read_b128 v[202:205], v152 offset:35840
	ds_read_b128 v[210:213], v152 offset:36864
	ds_read_b128 v[214:217], v152 offset:37888
	ds_read_b128 v[218:221], v152 offset:38912
	ds_read_b128 v[222:225], v152 offset:39936
	global_load_lds_dwordx4 v138, s[38:39]
	s_mov_b32 m0, s51
	s_nop 0
	global_load_lds_dwordx4 v136, s[38:39]
	s_waitcnt vmcnt(8)
	s_waitcnt lgkmcnt(0)
	s_setprio 1
	s_barrier
	v_mfma_f32_16x16x32_bf16 v[126:129], v[154:157], v[186:189], v[126:129]
	v_mfma_f32_16x16x32_bf16 v[122:125], v[162:165], v[186:189], v[122:125]
	v_mfma_f32_16x16x32_bf16 v[110:113], v[154:157], v[194:197], v[110:113]
	v_mfma_f32_16x16x32_bf16 v[106:109], v[162:165], v[194:197], v[106:109]
	v_mfma_f32_16x16x32_bf16 v[92:95], v[154:157], v[210:213], v[92:95]
	v_mfma_f32_16x16x32_bf16 v[88:91], v[162:165], v[210:213], v[88:91]
	v_mfma_f32_16x16x32_bf16 v[76:79], v[154:157], v[218:221], v[76:79]
	v_mfma_f32_16x16x32_bf16 v[72:75], v[162:165], v[218:221], v[72:75]
	v_mfma_f32_16x16x32_bf16 v[126:129], v[158:161], v[190:193], v[126:129]
	v_mfma_f32_16x16x32_bf16 v[122:125], v[166:169], v[190:193], v[122:125]
	v_mfma_f32_16x16x32_bf16 v[110:113], v[158:161], v[202:205], v[110:113]
	v_mfma_f32_16x16x32_bf16 v[106:109], v[166:169], v[202:205], v[106:109]
	v_mfma_f32_16x16x32_bf16 v[92:95], v[158:161], v[214:217], v[92:95]
	v_mfma_f32_16x16x32_bf16 v[88:91], v[166:169], v[214:217], v[88:91]
	v_mfma_f32_16x16x32_bf16 v[76:79], v[158:161], v[222:225], v[76:79]
	v_mfma_f32_16x16x32_bf16 v[72:75], v[166:169], v[222:225], v[72:75]
	v_mfma_f32_16x16x32_bf16 v[118:121], v[170:173], v[186:189], v[118:121]
	v_mfma_f32_16x16x32_bf16 v[114:117], v[178:181], v[186:189], v[114:117]
	v_mfma_f32_16x16x32_bf16 v[102:105], v[170:173], v[194:197], v[102:105]
	v_mfma_f32_16x16x32_bf16 v[98:101], v[178:181], v[194:197], v[98:101]
	v_mfma_f32_16x16x32_bf16 v[84:87], v[170:173], v[210:213], v[84:87]
	v_mfma_f32_16x16x32_bf16 v[80:83], v[178:181], v[210:213], v[80:83]
	v_mfma_f32_16x16x32_bf16 v[68:71], v[170:173], v[218:221], v[68:71]
	v_mfma_f32_16x16x32_bf16 v[64:67], v[178:181], v[218:221], v[64:67]
	v_mfma_f32_16x16x32_bf16 v[118:121], v[174:177], v[190:193], v[118:121]
	v_mfma_f32_16x16x32_bf16 v[114:117], v[182:185], v[190:193], v[114:117]
	v_mfma_f32_16x16x32_bf16 v[102:105], v[174:177], v[202:205], v[102:105]
	v_mfma_f32_16x16x32_bf16 v[98:101], v[182:185], v[202:205], v[98:101]
	v_mfma_f32_16x16x32_bf16 v[84:87], v[174:177], v[214:217], v[84:87]
	v_mfma_f32_16x16x32_bf16 v[80:83], v[182:185], v[214:217], v[80:83]
	v_mfma_f32_16x16x32_bf16 v[68:71], v[174:177], v[222:225], v[68:71]
	v_mfma_f32_16x16x32_bf16 v[64:67], v[182:185], v[222:225], v[64:67]
	s_barrier
	s_setprio 0
	s_add_i32 s33, s33, s75
	v_lshl_add_u64 v[144:145], v[144:145], 0, s[64:65]
	s_mov_b32 m0, s33
	ds_read_b128 v[186:189], v152 offset:49152
	ds_read_b128 v[190:193], v152 offset:50176
	ds_read_b128 v[194:197], v152 offset:51200
	ds_read_b128 v[202:205], v152 offset:52224
	ds_read_b128 v[210:213], v152 offset:53248
	ds_read_b128 v[214:217], v152 offset:54272
	ds_read_b128 v[218:221], v152 offset:55296
	ds_read_b128 v[222:225], v152 offset:56320
	global_load_lds_dwordx4 v[144:145], off
	s_add_i32 m0, s33, 0x2000
	s_add_u32 s38, s68, 0x80080
	v_lshl_add_u64 v[144:145], v[198:199], 0, s[64:65]
	s_addc_u32 s39, s69, 0
	s_add_i32 s33, s54, s75
	global_load_lds_dwordx4 v[144:145], off
	s_mov_b32 m0, s33
	s_nop 0
	global_load_lds_dwordx4 v96, s[38:39]
	s_add_i32 m0, s33, 0x2000
	s_nop 0
	global_load_lds_dwordx4 v134, s[38:39]
	v_lshl_add_u64 v[144:145], v[226:227], 0, s[64:65]
	s_mov_b32 m0, s58
	s_nop 0
	global_load_lds_dwordx4 v[144:145], off
	v_lshl_add_u64 v[144:145], v[228:229], 0, s[64:65]
	s_mov_b32 m0, s59
	s_nop 0
	global_load_lds_dwordx4 v[144:145], off
	s_waitcnt vmcnt(8)
	s_waitcnt lgkmcnt(0)
	s_setprio 1
	s_barrier
	v_mfma_f32_16x16x32_bf16 v[60:63], v[154:157], v[186:189], v[60:63]
	v_mfma_f32_16x16x32_bf16 v[56:59], v[162:165], v[186:189], v[56:59]
	v_mfma_f32_16x16x32_bf16 v[44:47], v[154:157], v[194:197], v[44:47]
	v_mfma_f32_16x16x32_bf16 v[40:43], v[162:165], v[194:197], v[40:43]
	v_mfma_f32_16x16x32_bf16 v[28:31], v[154:157], v[210:213], v[28:31]
	v_mfma_f32_16x16x32_bf16 v[24:27], v[162:165], v[210:213], v[24:27]
	v_mfma_f32_16x16x32_bf16 v[12:15], v[154:157], v[218:221], v[12:15]
	v_mfma_f32_16x16x32_bf16 v[8:11], v[162:165], v[218:221], v[8:11]
	v_mfma_f32_16x16x32_bf16 v[60:63], v[158:161], v[190:193], v[60:63]
	v_mfma_f32_16x16x32_bf16 v[56:59], v[166:169], v[190:193], v[56:59]
	v_mfma_f32_16x16x32_bf16 v[44:47], v[158:161], v[202:205], v[44:47]
	v_mfma_f32_16x16x32_bf16 v[40:43], v[166:169], v[202:205], v[40:43]
	v_mfma_f32_16x16x32_bf16 v[28:31], v[158:161], v[214:217], v[28:31]
	v_mfma_f32_16x16x32_bf16 v[24:27], v[166:169], v[214:217], v[24:27]
	v_mfma_f32_16x16x32_bf16 v[12:15], v[158:161], v[222:225], v[12:15]
	v_mfma_f32_16x16x32_bf16 v[8:11], v[166:169], v[222:225], v[8:11]
	v_mfma_f32_16x16x32_bf16 v[52:55], v[170:173], v[186:189], v[52:55]
	v_mfma_f32_16x16x32_bf16 v[48:51], v[178:181], v[186:189], v[48:51]
	v_mfma_f32_16x16x32_bf16 v[36:39], v[170:173], v[194:197], v[36:39]
	v_mfma_f32_16x16x32_bf16 v[32:35], v[178:181], v[194:197], v[32:35]
	v_mfma_f32_16x16x32_bf16 v[20:23], v[170:173], v[210:213], v[20:23]
	v_mfma_f32_16x16x32_bf16 v[16:19], v[178:181], v[210:213], v[16:19]
	v_mfma_f32_16x16x32_bf16 v[4:7], v[170:173], v[218:221], v[4:7]
	v_mfma_f32_16x16x32_bf16 v[0:3], v[178:181], v[218:221], v[0:3]
	v_mfma_f32_16x16x32_bf16 v[52:55], v[174:177], v[190:193], v[52:55]
	v_mfma_f32_16x16x32_bf16 v[48:51], v[182:185], v[190:193], v[48:51]
	v_mfma_f32_16x16x32_bf16 v[36:39], v[174:177], v[202:205], v[36:39]
	v_mfma_f32_16x16x32_bf16 v[32:35], v[182:185], v[202:205], v[32:35]
	v_mfma_f32_16x16x32_bf16 v[20:23], v[174:177], v[214:217], v[20:23]
	v_mfma_f32_16x16x32_bf16 v[16:19], v[182:185], v[214:217], v[16:19]
	v_mfma_f32_16x16x32_bf16 v[4:7], v[174:177], v[222:225], v[4:7]
	v_mfma_f32_16x16x32_bf16 v[0:3], v[182:185], v[222:225], v[0:3]
	s_barrier
	s_setprio 0
	s_add_i32 s28, s28, 2
	s_add_u32 s52, s52, 0x100
	s_addc_u32 s53, s53, 0
	s_add_u32 s20, s20, 0x100
	s_addc_u32 s25, s25, 0
	s_cmp_gt_u32 s28, 29
	s_cbranch_scc0 .LBB0_1284
	v_mov_b32_e32 v243, 1
	v_readlane_b32 s6, v251, 54
	v_readlane_b32 s7, v251, 55
	s_and_b64 vcc, exec, s[6:7]
	s_cbranch_vccz .LBB0_1287
	s_barrier
